# residual/final epilogue row reductions via v_permlane16_swap / v_permlane32_swap instead of ds_bpermute LDS round trips (bit-exact)
# baseline (speedup 1.0000x reference)
.Lg248_nox:
	v_and_b32_e32 v156, 64, v154
	v_xor_b32_e32 v155, 16, v154
	v_add_u32_e32 v156, 64, v156
	v_xor_b32_e32 v157, 32, v154
	v_cmp_lt_i32_e32 vcc, v155, v156
	s_lshl_b32 s20, s12, 2
	s_ashr_i32 s21, s20, 31
	v_cndmask_b32_e32 v155, v154, v155, vcc
	v_cmp_lt_i32_e32 vcc, v157, v156
	v_lshlrev_b32_e32 v156, 2, v155
	s_waitcnt vmcnt(14)
	v_lshlrev_b32_e32 v168, 16, v158
	v_and_b32_e32 v169, 0xffff0000, v158
	v_lshlrev_b32_e32 v158, 16, v159
	v_and_b32_e32 v159, 0xffff0000, v159
	v_lshlrev_b32_e32 v172, 16, v162
	v_and_b32_e32 v173, 0xffff0000, v162
	v_lshlrev_b32_e32 v162, 16, v163
	v_and_b32_e32 v163, 0xffff0000, v163
	v_cndmask_b32_e32 v157, v154, v157, vcc
	v_lshlrev_b32_e32 v170, 16, v160
	v_and_b32_e32 v171, 0xffff0000, v160
	v_lshlrev_b32_e32 v160, 16, v161
	v_and_b32_e32 v161, 0xffff0000, v161
	v_lshlrev_b32_e32 v174, 16, v164
	v_and_b32_e32 v175, 0xffff0000, v164
	v_lshlrev_b32_e32 v164, 16, v165
	v_and_b32_e32 v165, 0xffff0000, v165
	v_pk_fma_f32 v[126:127], v[126:127], 0.5, v[158:159] op_sel_hi:[1,0,1]
	v_pk_fma_f32 v[124:125], v[124:125], 0.5, v[168:169] op_sel_hi:[1,0,1]
	v_pk_fma_f32 v[118:119], v[118:119], 0.5, v[162:163] op_sel_hi:[1,0,1]
	v_pk_fma_f32 v[116:117], v[116:117], 0.5, v[172:173] op_sel_hi:[1,0,1]
	v_lshlrev_b32_e32 v155, 2, v157
	v_pk_fma_f32 v[122:123], v[122:123], 0.5, v[160:161] op_sel_hi:[1,0,1]
	v_pk_fma_f32 v[120:121], v[120:121], 0.5, v[170:171] op_sel_hi:[1,0,1]
	v_pk_fma_f32 v[158:159], v[114:115], 0.5, v[164:165] op_sel_hi:[1,0,1]
	v_pk_fma_f32 v[160:161], v[112:113], 0.5, v[174:175] op_sel_hi:[1,0,1]
	v_mul_f32_e32 v114, v125, v125
	v_mul_f32_e32 v115, v127, v127
	v_mul_f32_e32 v157, v117, v117
	v_mul_f32_e32 v162, v119, v119
	v_cvt_pk_bf16_f32 v112, v124, v125
	v_mul_f32_e32 v125, v121, v121
	v_mul_f32_e32 v163, v161, v161
	v_fmac_f32_e32 v114, v124, v124
	v_fmac_f32_e32 v115, v126, v126
	v_fmac_f32_e32 v157, v116, v116
	v_fmac_f32_e32 v162, v118, v118
	v_cvt_pk_bf16_f32 v113, v126, v127
	v_mul_f32_e32 v127, v123, v123
	v_mul_f32_e32 v164, v159, v159
	v_fmac_f32_e32 v125, v120, v120
	v_fmac_f32_e32 v163, v160, v160
	v_add_f32_e32 v114, v114, v115
	v_add_f32_e32 v115, v157, v162
	v_fmac_f32_e32 v127, v122, v122
	v_fmac_f32_e32 v164, v158, v158
	v_add_f32_e32 v114, v125, v114
	v_add_f32_e32 v115, v163, v115
	v_add_f32_e32 v114, v127, v114
	v_add_f32_e32 v115, v164, v115
	v_add_f32_e32 v124, v114, v115
	v_mov_b32_e32 v125, v124
	s_nop 1
	v_permlane16_swap_b32_e32 v125, v124
	v_cvt_pk_bf16_f32 v114, v120, v121
	v_cvt_pk_bf16_f32 v115, v122, v123
	global_store_dwordx4 v[166:167], v[112:115], off
	s_waitcnt lgkmcnt(0)
	s_nop 0
	v_add_f32_e32 v112, v124, v125
	v_mov_b32_e32 v113, v112
	s_nop 1
	v_permlane32_swap_b32_e32 v113, v112
	v_cvt_pk_bf16_f32 v114, v116, v117
	v_cvt_pk_bf16_f32 v115, v118, v119
	v_cvt_pk_bf16_f32 v116, v160, v161
	v_cvt_pk_bf16_f32 v117, v158, v159
	global_store_dwordx4 v[166:167], v[114:117], off offset:256
	s_and_saveexec_b64 s[26:27], s[4:5]
	s_cbranch_execz .LBB0_251
	v_lshlrev_b64 v[114:115], 6, v[146:147]
	v_lshl_add_u64 v[114:115], s[16:17], 0, v[114:115]
	v_lshl_add_u64 v[114:115], s[20:21], 2, v[114:115]
	s_lshl_b32 s12, s45, 2
	v_lshl_add_u64 v[114:115], v[114:115], 0, s[12:13]
	s_waitcnt lgkmcnt(0)
	v_add_f32_e32 v112, v112, v113
	global_store_dword v[114:115], v112, off
.LBB0_251:
	s_or_b64 exec, exec, s[26:27]
	v_or_b32_e32 v112, 16, v146
	s_waitcnt lgkmcnt(0)
	v_ashrrev_i32_e32 v113, 31, v112
	v_lshlrev_b64 v[114:115], 11, v[112:113]
	v_lshl_add_u64 v[114:115], s[14:15], 0, v[114:115]
	v_lshl_add_u64 v[122:123], v[144:145], 1, v[114:115]
	s_waitcnt vmcnt(15)
	v_lshlrev_b32_e32 v124, 16, v176
	v_and_b32_e32 v125, 0xffff0000, v176
	v_lshlrev_b32_e32 v114, 16, v177
	v_and_b32_e32 v115, 0xffff0000, v177
	s_waitcnt vmcnt(14)
	v_lshlrev_b32_e32 v158, 16, v180
	v_and_b32_e32 v159, 0xffff0000, v180
	v_lshlrev_b32_e32 v118, 16, v181
	v_and_b32_e32 v119, 0xffff0000, v181
	v_lshlrev_b32_e32 v126, 16, v178
	v_and_b32_e32 v127, 0xffff0000, v178
	v_lshlrev_b32_e32 v116, 16, v179
	v_and_b32_e32 v117, 0xffff0000, v179
	v_lshlrev_b32_e32 v160, 16, v182
	v_and_b32_e32 v161, 0xffff0000, v182
	v_lshlrev_b32_e32 v120, 16, v183
	v_and_b32_e32 v121, 0xffff0000, v183
	v_pk_fma_f32 v[110:111], v[110:111], 0.5, v[114:115] op_sel_hi:[1,0,1]
	v_pk_fma_f32 v[108:109], v[108:109], 0.5, v[124:125] op_sel_hi:[1,0,1]
	v_pk_fma_f32 v[102:103], v[102:103], 0.5, v[118:119] op_sel_hi:[1,0,1]
	v_pk_fma_f32 v[100:101], v[100:101], 0.5, v[158:159] op_sel_hi:[1,0,1]
	v_pk_fma_f32 v[106:107], v[106:107], 0.5, v[116:117] op_sel_hi:[1,0,1]
	v_pk_fma_f32 v[104:105], v[104:105], 0.5, v[126:127] op_sel_hi:[1,0,1]
	v_pk_fma_f32 v[114:115], v[98:99], 0.5, v[120:121] op_sel_hi:[1,0,1]
	v_pk_fma_f32 v[116:117], v[96:97], 0.5, v[160:161] op_sel_hi:[1,0,1]
	v_mul_f32_e32 v98, v109, v109
	v_mul_f32_e32 v99, v111, v111
	v_mul_f32_e32 v118, v101, v101
	v_mul_f32_e32 v119, v103, v103
	v_cvt_pk_bf16_f32 v96, v108, v109
	v_mul_f32_e32 v109, v105, v105
	v_mul_f32_e32 v120, v117, v117
	v_fmac_f32_e32 v98, v108, v108
	v_fmac_f32_e32 v99, v110, v110
	v_fmac_f32_e32 v118, v100, v100
	v_fmac_f32_e32 v119, v102, v102
	v_cvt_pk_bf16_f32 v97, v110, v111
	v_mul_f32_e32 v111, v107, v107
	v_mul_f32_e32 v121, v115, v115
	v_fmac_f32_e32 v109, v104, v104
	v_fmac_f32_e32 v120, v116, v116
	v_add_f32_e32 v98, v98, v99
	v_add_f32_e32 v99, v118, v119
	v_fmac_f32_e32 v111, v106, v106
	v_fmac_f32_e32 v121, v114, v114
	v_add_f32_e32 v98, v109, v98
	v_add_f32_e32 v99, v120, v99
	v_add_f32_e32 v98, v111, v98
	v_add_f32_e32 v99, v121, v99
	v_add_f32_e32 v108, v98, v99
	v_mov_b32_e32 v109, v108
	s_nop 1
	v_permlane16_swap_b32_e32 v109, v108
	v_cvt_pk_bf16_f32 v98, v104, v105
	v_cvt_pk_bf16_f32 v99, v106, v107
	global_store_dwordx4 v[122:123], v[96:99], off
	s_waitcnt lgkmcnt(0)
	s_nop 0
	v_add_f32_e32 v96, v108, v109
	v_mov_b32_e32 v97, v96
	s_nop 1
	v_permlane32_swap_b32_e32 v97, v96
	v_cvt_pk_bf16_f32 v98, v100, v101
	v_cvt_pk_bf16_f32 v99, v102, v103
	v_cvt_pk_bf16_f32 v100, v116, v117
	v_cvt_pk_bf16_f32 v101, v114, v115
	global_store_dwordx4 v[122:123], v[98:101], off offset:256
	s_and_saveexec_b64 s[26:27], s[4:5]
	s_cbranch_execz .LBB0_253
	v_lshlrev_b64 v[98:99], 6, v[112:113]
	v_lshl_add_u64 v[98:99], s[16:17], 0, v[98:99]
	v_lshl_add_u64 v[98:99], s[20:21], 2, v[98:99]
	s_lshl_b32 s12, s45, 2
	v_lshl_add_u64 v[98:99], v[98:99], 0, s[12:13]
	s_waitcnt lgkmcnt(0)
	v_add_f32_e32 v96, v96, v97
	global_store_dword v[98:99], v96, off
.LBB0_253:
	s_or_b64 exec, exec, s[26:27]
	v_or_b32_e32 v96, 32, v146
	s_waitcnt lgkmcnt(0)
	v_ashrrev_i32_e32 v97, 31, v96
	v_lshlrev_b64 v[98:99], 11, v[96:97]
	v_lshl_add_u64 v[98:99], s[14:15], 0, v[98:99]
	v_lshl_add_u64 v[106:107], v[144:145], 1, v[98:99]
	s_waitcnt vmcnt(15)
	v_lshlrev_b32_e32 v108, 16, v184
	v_and_b32_e32 v109, 0xffff0000, v184
	v_lshlrev_b32_e32 v98, 16, v185
	v_and_b32_e32 v99, 0xffff0000, v185
	s_waitcnt vmcnt(14)
	v_lshlrev_b32_e32 v112, 16, v188
	v_and_b32_e32 v113, 0xffff0000, v188
	v_lshlrev_b32_e32 v102, 16, v189
	v_and_b32_e32 v103, 0xffff0000, v189
	v_lshlrev_b32_e32 v110, 16, v186
	v_and_b32_e32 v111, 0xffff0000, v186
	v_lshlrev_b32_e32 v100, 16, v187
	v_and_b32_e32 v101, 0xffff0000, v187
	v_lshlrev_b32_e32 v114, 16, v190
	v_and_b32_e32 v115, 0xffff0000, v190
	v_lshlrev_b32_e32 v104, 16, v191
	v_and_b32_e32 v105, 0xffff0000, v191
	v_pk_fma_f32 v[94:95], v[94:95], 0.5, v[98:99] op_sel_hi:[1,0,1]
	v_pk_fma_f32 v[92:93], v[92:93], 0.5, v[108:109] op_sel_hi:[1,0,1]
	v_pk_fma_f32 v[86:87], v[86:87], 0.5, v[102:103] op_sel_hi:[1,0,1]
	v_pk_fma_f32 v[84:85], v[84:85], 0.5, v[112:113] op_sel_hi:[1,0,1]
	v_pk_fma_f32 v[90:91], v[90:91], 0.5, v[100:101] op_sel_hi:[1,0,1]
	v_pk_fma_f32 v[88:89], v[88:89], 0.5, v[110:111] op_sel_hi:[1,0,1]
	v_pk_fma_f32 v[98:99], v[82:83], 0.5, v[104:105] op_sel_hi:[1,0,1]
	v_pk_fma_f32 v[100:101], v[80:81], 0.5, v[114:115] op_sel_hi:[1,0,1]
	v_mul_f32_e32 v82, v93, v93
	v_mul_f32_e32 v83, v95, v95
	v_mul_f32_e32 v102, v85, v85
	v_mul_f32_e32 v103, v87, v87
	v_cvt_pk_bf16_f32 v80, v92, v93
	v_mul_f32_e32 v93, v89, v89
	v_mul_f32_e32 v104, v101, v101
	v_fmac_f32_e32 v82, v92, v92
	v_fmac_f32_e32 v83, v94, v94
	v_fmac_f32_e32 v102, v84, v84
	v_fmac_f32_e32 v103, v86, v86
	v_cvt_pk_bf16_f32 v81, v94, v95
	v_mul_f32_e32 v95, v91, v91
	v_mul_f32_e32 v105, v99, v99
	v_fmac_f32_e32 v93, v88, v88
	v_fmac_f32_e32 v104, v100, v100
	v_add_f32_e32 v82, v82, v83
	v_add_f32_e32 v83, v102, v103
	v_fmac_f32_e32 v95, v90, v90
	v_fmac_f32_e32 v105, v98, v98
	v_add_f32_e32 v82, v93, v82
	v_add_f32_e32 v83, v104, v83
	v_add_f32_e32 v82, v95, v82
	v_add_f32_e32 v83, v105, v83
	v_add_f32_e32 v92, v82, v83
	v_mov_b32_e32 v93, v92
	s_nop 1
	v_permlane16_swap_b32_e32 v93, v92
	v_cvt_pk_bf16_f32 v82, v88, v89
	v_cvt_pk_bf16_f32 v83, v90, v91
	global_store_dwordx4 v[106:107], v[80:83], off
	s_waitcnt lgkmcnt(0)
	s_nop 0
	v_add_f32_e32 v80, v92, v93
	v_mov_b32_e32 v81, v80
	s_nop 1
	v_permlane32_swap_b32_e32 v81, v80
	v_cvt_pk_bf16_f32 v82, v84, v85
	v_cvt_pk_bf16_f32 v83, v86, v87
	v_cvt_pk_bf16_f32 v84, v100, v101
	v_cvt_pk_bf16_f32 v85, v98, v99
	global_store_dwordx4 v[106:107], v[82:85], off offset:256
	s_and_saveexec_b64 s[26:27], s[4:5]
	s_cbranch_execz .LBB0_255
	v_lshlrev_b64 v[82:83], 6, v[96:97]
	v_lshl_add_u64 v[82:83], s[16:17], 0, v[82:83]
	v_lshl_add_u64 v[82:83], s[20:21], 2, v[82:83]
	s_lshl_b32 s12, s45, 2
	v_lshl_add_u64 v[82:83], v[82:83], 0, s[12:13]
	s_waitcnt lgkmcnt(0)
	v_add_f32_e32 v80, v80, v81
	global_store_dword v[82:83], v80, off
.LBB0_255:
	s_or_b64 exec, exec, s[26:27]
	v_or_b32_e32 v80, 48, v146
	s_waitcnt lgkmcnt(0)
	v_ashrrev_i32_e32 v81, 31, v80
	v_lshlrev_b64 v[82:83], 11, v[80:81]
	v_lshl_add_u64 v[82:83], s[14:15], 0, v[82:83]
	v_lshl_add_u64 v[90:91], v[144:145], 1, v[82:83]
	s_waitcnt vmcnt(15)
	v_lshlrev_b32_e32 v92, 16, v192
	v_and_b32_e32 v93, 0xffff0000, v192
	v_lshlrev_b32_e32 v82, 16, v193
	v_and_b32_e32 v83, 0xffff0000, v193
	s_waitcnt vmcnt(14)
	v_lshlrev_b32_e32 v96, 16, v196
	v_and_b32_e32 v97, 0xffff0000, v196
	v_lshlrev_b32_e32 v86, 16, v197
	v_and_b32_e32 v87, 0xffff0000, v197
	v_lshlrev_b32_e32 v94, 16, v194
	v_and_b32_e32 v95, 0xffff0000, v194
	v_lshlrev_b32_e32 v84, 16, v195
	v_and_b32_e32 v85, 0xffff0000, v195
	v_lshlrev_b32_e32 v98, 16, v198
	v_and_b32_e32 v99, 0xffff0000, v198
	v_lshlrev_b32_e32 v88, 16, v199
	v_and_b32_e32 v89, 0xffff0000, v199
	v_pk_fma_f32 v[78:79], v[78:79], 0.5, v[82:83] op_sel_hi:[1,0,1]
	v_pk_fma_f32 v[76:77], v[76:77], 0.5, v[92:93] op_sel_hi:[1,0,1]
	v_pk_fma_f32 v[70:71], v[70:71], 0.5, v[86:87] op_sel_hi:[1,0,1]
	v_pk_fma_f32 v[68:69], v[68:69], 0.5, v[96:97] op_sel_hi:[1,0,1]
	v_pk_fma_f32 v[74:75], v[74:75], 0.5, v[84:85] op_sel_hi:[1,0,1]
	v_pk_fma_f32 v[72:73], v[72:73], 0.5, v[94:95] op_sel_hi:[1,0,1]
	v_pk_fma_f32 v[82:83], v[66:67], 0.5, v[88:89] op_sel_hi:[1,0,1]
	v_pk_fma_f32 v[84:85], v[64:65], 0.5, v[98:99] op_sel_hi:[1,0,1]
	v_mul_f32_e32 v66, v77, v77
	v_mul_f32_e32 v67, v79, v79
	v_mul_f32_e32 v86, v69, v69
	v_mul_f32_e32 v87, v71, v71
	v_cvt_pk_bf16_f32 v64, v76, v77
	v_mul_f32_e32 v77, v73, v73
	v_mul_f32_e32 v88, v85, v85
	v_fmac_f32_e32 v66, v76, v76
	v_fmac_f32_e32 v67, v78, v78
	v_fmac_f32_e32 v86, v68, v68
	v_fmac_f32_e32 v87, v70, v70
	v_cvt_pk_bf16_f32 v65, v78, v79
	v_mul_f32_e32 v79, v75, v75
	v_mul_f32_e32 v89, v83, v83
	v_fmac_f32_e32 v77, v72, v72
	v_fmac_f32_e32 v88, v84, v84
	v_add_f32_e32 v66, v66, v67
	v_add_f32_e32 v67, v86, v87
	v_fmac_f32_e32 v79, v74, v74
	v_fmac_f32_e32 v89, v82, v82
	v_add_f32_e32 v66, v77, v66
	v_add_f32_e32 v67, v88, v67
	v_add_f32_e32 v66, v79, v66
	v_add_f32_e32 v67, v89, v67
	v_add_f32_e32 v76, v66, v67
	v_mov_b32_e32 v77, v76
	s_nop 1
	v_permlane16_swap_b32_e32 v77, v76
	v_cvt_pk_bf16_f32 v66, v72, v73
	v_cvt_pk_bf16_f32 v67, v74, v75
	global_store_dwordx4 v[90:91], v[64:67], off
	s_waitcnt lgkmcnt(0)
	s_nop 0
	v_add_f32_e32 v64, v76, v77
	v_mov_b32_e32 v65, v64
	s_nop 1
	v_permlane32_swap_b32_e32 v65, v64
	v_cvt_pk_bf16_f32 v66, v68, v69
	v_cvt_pk_bf16_f32 v67, v70, v71
	v_cvt_pk_bf16_f32 v68, v84, v85
	v_cvt_pk_bf16_f32 v69, v82, v83
	global_store_dwordx4 v[90:91], v[66:69], off offset:256
	s_and_saveexec_b64 s[26:27], s[4:5]
	s_cbranch_execz .LBB0_257
	v_lshlrev_b64 v[66:67], 6, v[80:81]
	v_lshl_add_u64 v[66:67], s[16:17], 0, v[66:67]
	v_lshl_add_u64 v[66:67], s[20:21], 2, v[66:67]
	s_lshl_b32 s12, s45, 2
	v_lshl_add_u64 v[66:67], v[66:67], 0, s[12:13]
	s_waitcnt lgkmcnt(0)
	v_add_f32_e32 v64, v64, v65
	global_store_dword v[66:67], v64, off
.LBB0_257:
	s_or_b64 exec, exec, s[26:27]
	v_add_u32_e32 v64, 0x80, v146
	s_waitcnt lgkmcnt(0)
	v_ashrrev_i32_e32 v65, 31, v64
	v_lshlrev_b64 v[66:67], 11, v[64:65]
	v_lshl_add_u64 v[66:67], s[14:15], 0, v[66:67]
	v_lshl_add_u64 v[74:75], v[144:145], 1, v[66:67]
	s_waitcnt vmcnt(15)
	v_lshlrev_b32_e32 v76, 16, v200
	v_and_b32_e32 v77, 0xffff0000, v200
	v_lshlrev_b32_e32 v66, 16, v201
	v_and_b32_e32 v67, 0xffff0000, v201
	s_waitcnt vmcnt(14)
	v_lshlrev_b32_e32 v80, 16, v204
	v_and_b32_e32 v81, 0xffff0000, v204
	v_lshlrev_b32_e32 v70, 16, v205
	v_and_b32_e32 v71, 0xffff0000, v205
	v_lshlrev_b32_e32 v78, 16, v202
	v_and_b32_e32 v79, 0xffff0000, v202
	v_lshlrev_b32_e32 v68, 16, v203
	v_and_b32_e32 v69, 0xffff0000, v203
	v_lshlrev_b32_e32 v82, 16, v206
	v_and_b32_e32 v83, 0xffff0000, v206
	v_lshlrev_b32_e32 v72, 16, v207
	v_and_b32_e32 v73, 0xffff0000, v207
	v_pk_fma_f32 v[62:63], v[62:63], 0.5, v[66:67] op_sel_hi:[1,0,1]
	v_pk_fma_f32 v[60:61], v[60:61], 0.5, v[76:77] op_sel_hi:[1,0,1]
	v_pk_fma_f32 v[54:55], v[54:55], 0.5, v[70:71] op_sel_hi:[1,0,1]
	v_pk_fma_f32 v[52:53], v[52:53], 0.5, v[80:81] op_sel_hi:[1,0,1]
	v_pk_fma_f32 v[58:59], v[58:59], 0.5, v[68:69] op_sel_hi:[1,0,1]
	v_pk_fma_f32 v[56:57], v[56:57], 0.5, v[78:79] op_sel_hi:[1,0,1]
	v_pk_fma_f32 v[66:67], v[50:51], 0.5, v[72:73] op_sel_hi:[1,0,1]
	v_pk_fma_f32 v[68:69], v[48:49], 0.5, v[82:83] op_sel_hi:[1,0,1]
	v_mul_f32_e32 v50, v61, v61
	v_mul_f32_e32 v51, v63, v63
	v_mul_f32_e32 v70, v53, v53
	v_mul_f32_e32 v71, v55, v55
	v_cvt_pk_bf16_f32 v48, v60, v61
	v_mul_f32_e32 v61, v57, v57
	v_mul_f32_e32 v72, v69, v69
	v_fmac_f32_e32 v50, v60, v60
	v_fmac_f32_e32 v51, v62, v62
	v_fmac_f32_e32 v70, v52, v52
	v_fmac_f32_e32 v71, v54, v54
	v_cvt_pk_bf16_f32 v49, v62, v63
	v_mul_f32_e32 v63, v59, v59
	v_mul_f32_e32 v73, v67, v67
	v_fmac_f32_e32 v61, v56, v56
	v_fmac_f32_e32 v72, v68, v68
	v_add_f32_e32 v50, v50, v51
	v_add_f32_e32 v51, v70, v71
	v_fmac_f32_e32 v63, v58, v58
	v_fmac_f32_e32 v73, v66, v66
	v_add_f32_e32 v50, v61, v50
	v_add_f32_e32 v51, v72, v51
	v_add_f32_e32 v50, v63, v50
	v_add_f32_e32 v51, v73, v51
	v_add_f32_e32 v60, v50, v51
	v_mov_b32_e32 v61, v60
	s_nop 1
	v_permlane16_swap_b32_e32 v61, v60
	v_cvt_pk_bf16_f32 v50, v56, v57
	v_cvt_pk_bf16_f32 v51, v58, v59
	global_store_dwordx4 v[74:75], v[48:51], off
	s_waitcnt lgkmcnt(0)
	s_nop 0
	v_add_f32_e32 v48, v60, v61
	v_mov_b32_e32 v49, v48
	s_nop 1
	v_permlane32_swap_b32_e32 v49, v48
	v_cvt_pk_bf16_f32 v50, v52, v53
	v_cvt_pk_bf16_f32 v51, v54, v55
	v_cvt_pk_bf16_f32 v52, v68, v69
	v_cvt_pk_bf16_f32 v53, v66, v67
	global_store_dwordx4 v[74:75], v[50:53], off offset:256
	s_and_saveexec_b64 s[26:27], s[4:5]
	s_cbranch_execz .LBB0_259
	v_lshlrev_b64 v[50:51], 6, v[64:65]
	v_lshl_add_u64 v[50:51], s[16:17], 0, v[50:51]
	v_lshl_add_u64 v[50:51], s[20:21], 2, v[50:51]
	s_lshl_b32 s12, s45, 2
	v_lshl_add_u64 v[50:51], v[50:51], 0, s[12:13]
	s_waitcnt lgkmcnt(0)
	v_add_f32_e32 v48, v48, v49
	global_store_dword v[50:51], v48, off
.LBB0_259:
	s_or_b64 exec, exec, s[26:27]
	v_add_u32_e32 v48, 0x90, v146
	s_waitcnt lgkmcnt(0)
	v_ashrrev_i32_e32 v49, 31, v48
	v_lshlrev_b64 v[50:51], 11, v[48:49]
	v_lshl_add_u64 v[50:51], s[14:15], 0, v[50:51]
	v_lshl_add_u64 v[58:59], v[144:145], 1, v[50:51]
	s_waitcnt vmcnt(15)
	v_lshlrev_b32_e32 v60, 16, v208
	v_and_b32_e32 v61, 0xffff0000, v208
	v_lshlrev_b32_e32 v50, 16, v209
	v_and_b32_e32 v51, 0xffff0000, v209
	s_waitcnt vmcnt(14)
	v_lshlrev_b32_e32 v64, 16, v212
	v_and_b32_e32 v65, 0xffff0000, v212
	v_lshlrev_b32_e32 v54, 16, v213
	v_and_b32_e32 v55, 0xffff0000, v213
	v_lshlrev_b32_e32 v62, 16, v210
	v_and_b32_e32 v63, 0xffff0000, v210
	v_lshlrev_b32_e32 v52, 16, v211
	v_and_b32_e32 v53, 0xffff0000, v211
	v_lshlrev_b32_e32 v66, 16, v214
	v_and_b32_e32 v67, 0xffff0000, v214
	v_lshlrev_b32_e32 v56, 16, v215
	v_and_b32_e32 v57, 0xffff0000, v215
	v_pk_fma_f32 v[46:47], v[46:47], 0.5, v[50:51] op_sel_hi:[1,0,1]
	v_pk_fma_f32 v[44:45], v[44:45], 0.5, v[60:61] op_sel_hi:[1,0,1]
	v_pk_fma_f32 v[38:39], v[38:39], 0.5, v[54:55] op_sel_hi:[1,0,1]
	v_pk_fma_f32 v[36:37], v[36:37], 0.5, v[64:65] op_sel_hi:[1,0,1]
	v_pk_fma_f32 v[42:43], v[42:43], 0.5, v[52:53] op_sel_hi:[1,0,1]
	v_pk_fma_f32 v[40:41], v[40:41], 0.5, v[62:63] op_sel_hi:[1,0,1]
	v_pk_fma_f32 v[50:51], v[34:35], 0.5, v[56:57] op_sel_hi:[1,0,1]
	v_pk_fma_f32 v[52:53], v[32:33], 0.5, v[66:67] op_sel_hi:[1,0,1]
	v_mul_f32_e32 v34, v45, v45
	v_mul_f32_e32 v35, v47, v47
	v_mul_f32_e32 v54, v37, v37
	v_mul_f32_e32 v55, v39, v39
	v_cvt_pk_bf16_f32 v32, v44, v45
	v_mul_f32_e32 v45, v41, v41
	v_mul_f32_e32 v56, v53, v53
	v_fmac_f32_e32 v34, v44, v44
	v_fmac_f32_e32 v35, v46, v46
	v_fmac_f32_e32 v54, v36, v36
	v_fmac_f32_e32 v55, v38, v38
	v_cvt_pk_bf16_f32 v33, v46, v47
	v_mul_f32_e32 v47, v43, v43
	v_mul_f32_e32 v57, v51, v51
	v_fmac_f32_e32 v45, v40, v40
	v_fmac_f32_e32 v56, v52, v52
	v_add_f32_e32 v34, v34, v35
	v_add_f32_e32 v35, v54, v55
	v_fmac_f32_e32 v47, v42, v42
	v_fmac_f32_e32 v57, v50, v50
	v_add_f32_e32 v34, v45, v34
	v_add_f32_e32 v35, v56, v35
	v_add_f32_e32 v34, v47, v34
	v_add_f32_e32 v35, v57, v35
	v_add_f32_e32 v44, v34, v35
	v_mov_b32_e32 v45, v44
	s_nop 1
	v_permlane16_swap_b32_e32 v45, v44
	v_cvt_pk_bf16_f32 v34, v40, v41
	v_cvt_pk_bf16_f32 v35, v42, v43
	global_store_dwordx4 v[58:59], v[32:35], off
	s_waitcnt lgkmcnt(0)
	s_nop 0
	v_add_f32_e32 v32, v44, v45
	v_mov_b32_e32 v33, v32
	s_nop 1
	v_permlane32_swap_b32_e32 v33, v32
	v_cvt_pk_bf16_f32 v34, v36, v37
	v_cvt_pk_bf16_f32 v35, v38, v39
	v_cvt_pk_bf16_f32 v36, v52, v53
	v_cvt_pk_bf16_f32 v37, v50, v51
	global_store_dwordx4 v[58:59], v[34:37], off offset:256
	s_and_saveexec_b64 s[26:27], s[4:5]
	s_cbranch_execz .LBB0_261
	v_lshlrev_b64 v[34:35], 6, v[48:49]
	v_lshl_add_u64 v[34:35], s[16:17], 0, v[34:35]
	v_lshl_add_u64 v[34:35], s[20:21], 2, v[34:35]
	s_lshl_b32 s12, s45, 2
	v_lshl_add_u64 v[34:35], v[34:35], 0, s[12:13]
	s_waitcnt lgkmcnt(0)
	v_add_f32_e32 v32, v32, v33
	global_store_dword v[34:35], v32, off
.LBB0_261:
	s_or_b64 exec, exec, s[26:27]
	v_add_u32_e32 v32, 0xa0, v146
	s_waitcnt lgkmcnt(0)
	v_ashrrev_i32_e32 v33, 31, v32
	v_lshlrev_b64 v[34:35], 11, v[32:33]
	v_lshl_add_u64 v[34:35], s[14:15], 0, v[34:35]
	v_lshl_add_u64 v[42:43], v[144:145], 1, v[34:35]
	s_waitcnt vmcnt(15)
	v_lshlrev_b32_e32 v44, 16, v216
	v_and_b32_e32 v45, 0xffff0000, v216
	v_lshlrev_b32_e32 v34, 16, v217
	v_and_b32_e32 v35, 0xffff0000, v217
	s_waitcnt vmcnt(14)
	v_lshlrev_b32_e32 v48, 16, v220
	v_and_b32_e32 v49, 0xffff0000, v220
	v_lshlrev_b32_e32 v38, 16, v221
	v_and_b32_e32 v39, 0xffff0000, v221
	v_lshlrev_b32_e32 v46, 16, v218
	v_and_b32_e32 v47, 0xffff0000, v218
	v_lshlrev_b32_e32 v36, 16, v219
	v_and_b32_e32 v37, 0xffff0000, v219
	v_lshlrev_b32_e32 v50, 16, v222
	v_and_b32_e32 v51, 0xffff0000, v222
	v_lshlrev_b32_e32 v40, 16, v223
	v_and_b32_e32 v41, 0xffff0000, v223
	v_pk_fma_f32 v[30:31], v[30:31], 0.5, v[34:35] op_sel_hi:[1,0,1]
	v_pk_fma_f32 v[28:29], v[28:29], 0.5, v[44:45] op_sel_hi:[1,0,1]
	v_pk_fma_f32 v[22:23], v[22:23], 0.5, v[38:39] op_sel_hi:[1,0,1]
	v_pk_fma_f32 v[20:21], v[20:21], 0.5, v[48:49] op_sel_hi:[1,0,1]
	v_pk_fma_f32 v[26:27], v[26:27], 0.5, v[36:37] op_sel_hi:[1,0,1]
	v_pk_fma_f32 v[24:25], v[24:25], 0.5, v[46:47] op_sel_hi:[1,0,1]
	v_pk_fma_f32 v[34:35], v[18:19], 0.5, v[40:41] op_sel_hi:[1,0,1]
	v_pk_fma_f32 v[36:37], v[16:17], 0.5, v[50:51] op_sel_hi:[1,0,1]
	v_mul_f32_e32 v18, v29, v29
	v_mul_f32_e32 v19, v31, v31
	v_mul_f32_e32 v38, v21, v21
	v_mul_f32_e32 v39, v23, v23
	v_cvt_pk_bf16_f32 v16, v28, v29
	v_mul_f32_e32 v29, v25, v25
	v_mul_f32_e32 v40, v37, v37
	v_fmac_f32_e32 v18, v28, v28
	v_fmac_f32_e32 v19, v30, v30
	v_fmac_f32_e32 v38, v20, v20
	v_fmac_f32_e32 v39, v22, v22
	v_cvt_pk_bf16_f32 v17, v30, v31
	v_mul_f32_e32 v31, v27, v27
	v_mul_f32_e32 v41, v35, v35
	v_fmac_f32_e32 v29, v24, v24
	v_fmac_f32_e32 v40, v36, v36
	v_add_f32_e32 v18, v18, v19
	v_add_f32_e32 v19, v38, v39
	v_fmac_f32_e32 v31, v26, v26
	v_fmac_f32_e32 v41, v34, v34
	v_add_f32_e32 v18, v29, v18
	v_add_f32_e32 v19, v40, v19
	v_add_f32_e32 v18, v31, v18
	v_add_f32_e32 v19, v41, v19
	v_add_f32_e32 v28, v18, v19
	v_mov_b32_e32 v29, v28
	s_nop 1
	v_permlane16_swap_b32_e32 v29, v28
	v_cvt_pk_bf16_f32 v18, v24, v25
	v_cvt_pk_bf16_f32 v19, v26, v27
	global_store_dwordx4 v[42:43], v[16:19], off
	s_waitcnt lgkmcnt(0)
	s_nop 0
	v_add_f32_e32 v16, v28, v29
	v_mov_b32_e32 v17, v16
	s_nop 1
	v_permlane32_swap_b32_e32 v17, v16
	v_cvt_pk_bf16_f32 v18, v20, v21
	v_cvt_pk_bf16_f32 v19, v22, v23
	v_cvt_pk_bf16_f32 v20, v36, v37
	v_cvt_pk_bf16_f32 v21, v34, v35
	global_store_dwordx4 v[42:43], v[18:21], off offset:256
	s_and_saveexec_b64 s[26:27], s[4:5]
	s_cbranch_execz .LBB0_263
	v_lshlrev_b64 v[18:19], 6, v[32:33]
	v_lshl_add_u64 v[18:19], s[16:17], 0, v[18:19]
	v_lshl_add_u64 v[18:19], s[20:21], 2, v[18:19]
	s_lshl_b32 s12, s45, 2
	v_lshl_add_u64 v[18:19], v[18:19], 0, s[12:13]
	s_waitcnt lgkmcnt(0)
	v_add_f32_e32 v16, v16, v17
	global_store_dword v[18:19], v16, off
.LBB0_263:
	s_or_b64 exec, exec, s[26:27]
	v_add_u32_e32 v16, 0xb0, v146
	s_waitcnt lgkmcnt(0)
	v_ashrrev_i32_e32 v17, 31, v16
	v_lshlrev_b64 v[18:19], 11, v[16:17]
	v_lshl_add_u64 v[18:19], s[14:15], 0, v[18:19]
	v_lshl_add_u64 v[26:27], v[144:145], 1, v[18:19]
	s_waitcnt vmcnt(15)
	v_lshlrev_b32_e32 v28, 16, v224
	v_and_b32_e32 v29, 0xffff0000, v224
	v_lshlrev_b32_e32 v18, 16, v225
	v_and_b32_e32 v19, 0xffff0000, v225
	s_waitcnt vmcnt(14)
	v_lshlrev_b32_e32 v32, 16, v228
	v_and_b32_e32 v33, 0xffff0000, v228
	v_lshlrev_b32_e32 v22, 16, v229
	v_and_b32_e32 v23, 0xffff0000, v229
	v_lshlrev_b32_e32 v30, 16, v226
	v_and_b32_e32 v31, 0xffff0000, v226
	v_lshlrev_b32_e32 v20, 16, v227
	v_and_b32_e32 v21, 0xffff0000, v227
	v_lshlrev_b32_e32 v34, 16, v230
	v_and_b32_e32 v35, 0xffff0000, v230
	v_lshlrev_b32_e32 v24, 16, v231
	v_and_b32_e32 v25, 0xffff0000, v231
	v_pk_fma_f32 v[14:15], v[14:15], 0.5, v[18:19] op_sel_hi:[1,0,1]
	v_pk_fma_f32 v[12:13], v[12:13], 0.5, v[28:29] op_sel_hi:[1,0,1]
	v_pk_fma_f32 v[6:7], v[6:7], 0.5, v[22:23] op_sel_hi:[1,0,1]
	v_pk_fma_f32 v[4:5], v[4:5], 0.5, v[32:33] op_sel_hi:[1,0,1]
	v_pk_fma_f32 v[10:11], v[10:11], 0.5, v[20:21] op_sel_hi:[1,0,1]
	v_pk_fma_f32 v[8:9], v[8:9], 0.5, v[30:31] op_sel_hi:[1,0,1]
	v_pk_fma_f32 v[18:19], v[2:3], 0.5, v[24:25] op_sel_hi:[1,0,1]
	v_pk_fma_f32 v[20:21], v[0:1], 0.5, v[34:35] op_sel_hi:[1,0,1]
	v_mul_f32_e32 v2, v13, v13
	v_mul_f32_e32 v3, v15, v15
	v_mul_f32_e32 v22, v5, v5
	v_mul_f32_e32 v23, v7, v7
	v_cvt_pk_bf16_f32 v0, v12, v13
	v_mul_f32_e32 v13, v9, v9
	v_mul_f32_e32 v24, v21, v21
	v_fmac_f32_e32 v2, v12, v12
	v_fmac_f32_e32 v3, v14, v14
	v_fmac_f32_e32 v22, v4, v4
	v_fmac_f32_e32 v23, v6, v6
	v_cvt_pk_bf16_f32 v1, v14, v15
	v_mul_f32_e32 v15, v11, v11
	v_mul_f32_e32 v25, v19, v19
	v_fmac_f32_e32 v13, v8, v8
	v_fmac_f32_e32 v24, v20, v20
	v_add_f32_e32 v2, v2, v3
	v_add_f32_e32 v3, v22, v23
	v_fmac_f32_e32 v15, v10, v10
	v_fmac_f32_e32 v25, v18, v18
	v_add_f32_e32 v2, v13, v2
	v_add_f32_e32 v3, v24, v3
	v_add_f32_e32 v2, v15, v2
	v_add_f32_e32 v3, v25, v3
	v_add_f32_e32 v12, v2, v3
	v_mov_b32_e32 v13, v12
	s_nop 1
	v_permlane16_swap_b32_e32 v13, v12
	v_cvt_pk_bf16_f32 v2, v8, v9
	v_cvt_pk_bf16_f32 v3, v10, v11
	global_store_dwordx4 v[26:27], v[0:3], off
	s_waitcnt lgkmcnt(0)
	s_nop 0
	v_add_f32_e32 v0, v12, v13
	v_mov_b32_e32 v1, v0
	s_nop 1
	v_permlane32_swap_b32_e32 v1, v0
	v_cvt_pk_bf16_f32 v2, v4, v5
	v_cvt_pk_bf16_f32 v3, v6, v7
	v_cvt_pk_bf16_f32 v4, v20, v21
	v_cvt_pk_bf16_f32 v5, v18, v19
	global_store_dwordx4 v[26:27], v[2:5], off offset:256
	s_and_saveexec_b64 s[26:27], s[4:5]
	s_cbranch_execz .LBB0_240
	v_lshlrev_b64 v[2:3], 6, v[16:17]
	v_lshl_add_u64 v[2:3], s[16:17], 0, v[2:3]
	v_lshl_add_u64 v[2:3], s[20:21], 2, v[2:3]
	s_lshl_b32 s12, s45, 2
	v_lshl_add_u64 v[2:3], v[2:3], 0, s[12:13]
	s_waitcnt lgkmcnt(0)
	v_add_f32_e32 v0, v0, v1
	global_store_dword v[2:3], v0, off
	s_branch .LBB0_240

.Lg786_nox:
	v_and_b32_e32 v156, 64, v154
	v_xor_b32_e32 v155, 16, v154
	v_add_u32_e32 v156, 64, v156
	v_xor_b32_e32 v157, 32, v154
	v_cmp_lt_i32_e32 vcc, v155, v156
	s_lshl_b32 s28, s56, 2
	s_ashr_i32 s29, s28, 31
	v_cndmask_b32_e32 v155, v154, v155, vcc
	v_cmp_lt_i32_e32 vcc, v157, v156
	v_lshlrev_b32_e32 v156, 2, v155
	s_waitcnt vmcnt(14)
	v_lshlrev_b32_e32 v168, 16, v158
	v_and_b32_e32 v169, 0xffff0000, v158
	v_lshlrev_b32_e32 v158, 16, v159
	v_and_b32_e32 v159, 0xffff0000, v159
	v_lshlrev_b32_e32 v172, 16, v162
	v_and_b32_e32 v173, 0xffff0000, v162
	v_lshlrev_b32_e32 v162, 16, v163
	v_and_b32_e32 v163, 0xffff0000, v163
	v_cndmask_b32_e32 v157, v154, v157, vcc
	v_lshlrev_b32_e32 v170, 16, v160
	v_and_b32_e32 v171, 0xffff0000, v160
	v_lshlrev_b32_e32 v160, 16, v161
	v_and_b32_e32 v161, 0xffff0000, v161
	v_lshlrev_b32_e32 v174, 16, v164
	v_and_b32_e32 v175, 0xffff0000, v164
	v_lshlrev_b32_e32 v164, 16, v165
	v_and_b32_e32 v165, 0xffff0000, v165
	v_pk_add_f32 v[126:127], v[126:127], v[158:159]
	v_pk_add_f32 v[124:125], v[124:125], v[168:169]
	v_pk_add_f32 v[118:119], v[118:119], v[162:163]
	v_pk_add_f32 v[116:117], v[116:117], v[172:173]
	v_lshlrev_b32_e32 v155, 2, v157
	v_pk_add_f32 v[122:123], v[122:123], v[160:161]
	v_pk_add_f32 v[120:121], v[120:121], v[170:171]
	v_pk_add_f32 v[158:159], v[114:115], v[164:165]
	v_pk_add_f32 v[160:161], v[112:113], v[174:175]
	v_mul_f32_e32 v114, v125, v125
	v_mul_f32_e32 v115, v127, v127
	v_mul_f32_e32 v157, v117, v117
	v_mul_f32_e32 v162, v119, v119
	v_cvt_pk_bf16_f32 v112, v124, v125
	v_mul_f32_e32 v125, v121, v121
	v_mul_f32_e32 v163, v161, v161
	v_fmac_f32_e32 v114, v124, v124
	v_fmac_f32_e32 v115, v126, v126
	v_fmac_f32_e32 v157, v116, v116
	v_fmac_f32_e32 v162, v118, v118
	v_cvt_pk_bf16_f32 v113, v126, v127
	v_mul_f32_e32 v127, v123, v123
	v_mul_f32_e32 v164, v159, v159
	v_fmac_f32_e32 v125, v120, v120
	v_fmac_f32_e32 v163, v160, v160
	v_add_f32_e32 v114, v114, v115
	v_add_f32_e32 v115, v157, v162
	v_fmac_f32_e32 v127, v122, v122
	v_fmac_f32_e32 v164, v158, v158
	v_add_f32_e32 v114, v125, v114
	v_add_f32_e32 v115, v163, v115
	v_add_f32_e32 v114, v127, v114
	v_add_f32_e32 v115, v164, v115
	v_add_f32_e32 v124, v114, v115
	v_mov_b32_e32 v125, v124
	s_nop 1
	v_permlane16_swap_b32_e32 v125, v124
	v_cvt_pk_bf16_f32 v114, v120, v121
	v_cvt_pk_bf16_f32 v115, v122, v123
	global_store_dwordx4 v[166:167], v[112:115], off
	s_waitcnt lgkmcnt(0)
	s_nop 0
	v_add_f32_e32 v112, v124, v125
	v_mov_b32_e32 v113, v112
	s_nop 1
	v_permlane32_swap_b32_e32 v113, v112
	v_cvt_pk_bf16_f32 v114, v116, v117
	v_cvt_pk_bf16_f32 v115, v118, v119
	v_cvt_pk_bf16_f32 v116, v160, v161
	v_cvt_pk_bf16_f32 v117, v158, v159
	global_store_dwordx4 v[166:167], v[114:117], off offset:256
	s_and_saveexec_b64 s[30:31], s[4:5]
	s_cbranch_execz .LBB0_789
	v_lshlrev_b64 v[114:115], 6, v[146:147]
	v_lshl_add_u64 v[114:115], s[12:13], 0, v[114:115]
	v_lshl_add_u64 v[114:115], s[28:29], 2, v[114:115]
	s_lshl_b32 s8, s49, 2
	v_lshl_add_u64 v[114:115], v[114:115], 0, s[8:9]
	s_waitcnt lgkmcnt(0)
	v_add_f32_e32 v112, v112, v113
	global_store_dword v[114:115], v112, off
.LBB0_789:
	s_or_b64 exec, exec, s[30:31]
	v_or_b32_e32 v112, 16, v146
	s_waitcnt lgkmcnt(0)
	v_ashrrev_i32_e32 v113, 31, v112
	v_lshlrev_b64 v[114:115], 11, v[112:113]
	v_lshl_add_u64 v[114:115], s[10:11], 0, v[114:115]
	v_lshl_add_u64 v[122:123], v[144:145], 1, v[114:115]
	s_waitcnt vmcnt(15)
	v_lshlrev_b32_e32 v124, 16, v176
	v_and_b32_e32 v125, 0xffff0000, v176
	v_lshlrev_b32_e32 v114, 16, v177
	v_and_b32_e32 v115, 0xffff0000, v177
	s_waitcnt vmcnt(14)
	v_lshlrev_b32_e32 v158, 16, v180
	v_and_b32_e32 v159, 0xffff0000, v180
	v_lshlrev_b32_e32 v118, 16, v181
	v_and_b32_e32 v119, 0xffff0000, v181
	v_lshlrev_b32_e32 v126, 16, v178
	v_and_b32_e32 v127, 0xffff0000, v178
	v_lshlrev_b32_e32 v116, 16, v179
	v_and_b32_e32 v117, 0xffff0000, v179
	v_lshlrev_b32_e32 v160, 16, v182
	v_and_b32_e32 v161, 0xffff0000, v182
	v_lshlrev_b32_e32 v120, 16, v183
	v_and_b32_e32 v121, 0xffff0000, v183
	v_pk_add_f32 v[110:111], v[110:111], v[114:115]
	v_pk_add_f32 v[108:109], v[108:109], v[124:125]
	v_pk_add_f32 v[102:103], v[102:103], v[118:119]
	v_pk_add_f32 v[100:101], v[100:101], v[158:159]
	v_pk_add_f32 v[106:107], v[106:107], v[116:117]
	v_pk_add_f32 v[104:105], v[104:105], v[126:127]
	v_pk_add_f32 v[114:115], v[98:99], v[120:121]
	v_pk_add_f32 v[116:117], v[96:97], v[160:161]
	v_mul_f32_e32 v98, v109, v109
	v_mul_f32_e32 v99, v111, v111
	v_mul_f32_e32 v118, v101, v101
	v_mul_f32_e32 v119, v103, v103
	v_cvt_pk_bf16_f32 v96, v108, v109
	v_mul_f32_e32 v109, v105, v105
	v_mul_f32_e32 v120, v117, v117
	v_fmac_f32_e32 v98, v108, v108
	v_fmac_f32_e32 v99, v110, v110
	v_fmac_f32_e32 v118, v100, v100
	v_fmac_f32_e32 v119, v102, v102
	v_cvt_pk_bf16_f32 v97, v110, v111
	v_mul_f32_e32 v111, v107, v107
	v_mul_f32_e32 v121, v115, v115
	v_fmac_f32_e32 v109, v104, v104
	v_fmac_f32_e32 v120, v116, v116
	v_add_f32_e32 v98, v98, v99
	v_add_f32_e32 v99, v118, v119
	v_fmac_f32_e32 v111, v106, v106
	v_fmac_f32_e32 v121, v114, v114
	v_add_f32_e32 v98, v109, v98
	v_add_f32_e32 v99, v120, v99
	v_add_f32_e32 v98, v111, v98
	v_add_f32_e32 v99, v121, v99
	v_add_f32_e32 v108, v98, v99
	v_mov_b32_e32 v109, v108
	s_nop 1
	v_permlane16_swap_b32_e32 v109, v108
	v_cvt_pk_bf16_f32 v98, v104, v105
	v_cvt_pk_bf16_f32 v99, v106, v107
	global_store_dwordx4 v[122:123], v[96:99], off
	s_waitcnt lgkmcnt(0)
	s_nop 0
	v_add_f32_e32 v96, v108, v109
	v_mov_b32_e32 v97, v96
	s_nop 1
	v_permlane32_swap_b32_e32 v97, v96
	v_cvt_pk_bf16_f32 v98, v100, v101
	v_cvt_pk_bf16_f32 v99, v102, v103
	v_cvt_pk_bf16_f32 v100, v116, v117
	v_cvt_pk_bf16_f32 v101, v114, v115
	global_store_dwordx4 v[122:123], v[98:101], off offset:256
	s_and_saveexec_b64 s[30:31], s[4:5]
	s_cbranch_execz .LBB0_791
	v_lshlrev_b64 v[98:99], 6, v[112:113]
	v_lshl_add_u64 v[98:99], s[12:13], 0, v[98:99]
	v_lshl_add_u64 v[98:99], s[28:29], 2, v[98:99]
	s_lshl_b32 s8, s49, 2
	v_lshl_add_u64 v[98:99], v[98:99], 0, s[8:9]
	s_waitcnt lgkmcnt(0)
	v_add_f32_e32 v96, v96, v97
	global_store_dword v[98:99], v96, off
.LBB0_791:
	s_or_b64 exec, exec, s[30:31]
	v_or_b32_e32 v96, 32, v146
	s_waitcnt lgkmcnt(0)
	v_ashrrev_i32_e32 v97, 31, v96
	v_lshlrev_b64 v[98:99], 11, v[96:97]
	v_lshl_add_u64 v[98:99], s[10:11], 0, v[98:99]
	v_lshl_add_u64 v[106:107], v[144:145], 1, v[98:99]
	s_waitcnt vmcnt(15)
	v_lshlrev_b32_e32 v108, 16, v184
	v_and_b32_e32 v109, 0xffff0000, v184
	v_lshlrev_b32_e32 v98, 16, v185
	v_and_b32_e32 v99, 0xffff0000, v185
	s_waitcnt vmcnt(14)
	v_lshlrev_b32_e32 v112, 16, v188
	v_and_b32_e32 v113, 0xffff0000, v188
	v_lshlrev_b32_e32 v102, 16, v189
	v_and_b32_e32 v103, 0xffff0000, v189
	v_lshlrev_b32_e32 v110, 16, v186
	v_and_b32_e32 v111, 0xffff0000, v186
	v_lshlrev_b32_e32 v100, 16, v187
	v_and_b32_e32 v101, 0xffff0000, v187
	v_lshlrev_b32_e32 v114, 16, v190
	v_and_b32_e32 v115, 0xffff0000, v190
	v_lshlrev_b32_e32 v104, 16, v191
	v_and_b32_e32 v105, 0xffff0000, v191
	v_pk_add_f32 v[94:95], v[94:95], v[98:99]
	v_pk_add_f32 v[92:93], v[92:93], v[108:109]
	v_pk_add_f32 v[86:87], v[86:87], v[102:103]
	v_pk_add_f32 v[84:85], v[84:85], v[112:113]
	v_pk_add_f32 v[90:91], v[90:91], v[100:101]
	v_pk_add_f32 v[88:89], v[88:89], v[110:111]
	v_pk_add_f32 v[98:99], v[82:83], v[104:105]
	v_pk_add_f32 v[100:101], v[80:81], v[114:115]
	v_mul_f32_e32 v82, v93, v93
	v_mul_f32_e32 v83, v95, v95
	v_mul_f32_e32 v102, v85, v85
	v_mul_f32_e32 v103, v87, v87
	v_cvt_pk_bf16_f32 v80, v92, v93
	v_mul_f32_e32 v93, v89, v89
	v_mul_f32_e32 v104, v101, v101
	v_fmac_f32_e32 v82, v92, v92
	v_fmac_f32_e32 v83, v94, v94
	v_fmac_f32_e32 v102, v84, v84
	v_fmac_f32_e32 v103, v86, v86
	v_cvt_pk_bf16_f32 v81, v94, v95
	v_mul_f32_e32 v95, v91, v91
	v_mul_f32_e32 v105, v99, v99
	v_fmac_f32_e32 v93, v88, v88
	v_fmac_f32_e32 v104, v100, v100
	v_add_f32_e32 v82, v82, v83
	v_add_f32_e32 v83, v102, v103
	v_fmac_f32_e32 v95, v90, v90
	v_fmac_f32_e32 v105, v98, v98
	v_add_f32_e32 v82, v93, v82
	v_add_f32_e32 v83, v104, v83
	v_add_f32_e32 v82, v95, v82
	v_add_f32_e32 v83, v105, v83
	v_add_f32_e32 v92, v82, v83
	v_mov_b32_e32 v93, v92
	s_nop 1
	v_permlane16_swap_b32_e32 v93, v92
	v_cvt_pk_bf16_f32 v82, v88, v89
	v_cvt_pk_bf16_f32 v83, v90, v91
	global_store_dwordx4 v[106:107], v[80:83], off
	s_waitcnt lgkmcnt(0)
	s_nop 0
	v_add_f32_e32 v80, v92, v93
	v_mov_b32_e32 v81, v80
	s_nop 1
	v_permlane32_swap_b32_e32 v81, v80
	v_cvt_pk_bf16_f32 v82, v84, v85
	v_cvt_pk_bf16_f32 v83, v86, v87
	v_cvt_pk_bf16_f32 v84, v100, v101
	v_cvt_pk_bf16_f32 v85, v98, v99
	global_store_dwordx4 v[106:107], v[82:85], off offset:256
	s_and_saveexec_b64 s[30:31], s[4:5]
	s_cbranch_execz .LBB0_793
	v_lshlrev_b64 v[82:83], 6, v[96:97]
	v_lshl_add_u64 v[82:83], s[12:13], 0, v[82:83]
	v_lshl_add_u64 v[82:83], s[28:29], 2, v[82:83]
	s_lshl_b32 s8, s49, 2
	v_lshl_add_u64 v[82:83], v[82:83], 0, s[8:9]
	s_waitcnt lgkmcnt(0)
	v_add_f32_e32 v80, v80, v81
	global_store_dword v[82:83], v80, off
.LBB0_793:
	s_or_b64 exec, exec, s[30:31]
	v_or_b32_e32 v80, 48, v146
	s_waitcnt lgkmcnt(0)
	v_ashrrev_i32_e32 v81, 31, v80
	v_lshlrev_b64 v[82:83], 11, v[80:81]
	v_lshl_add_u64 v[82:83], s[10:11], 0, v[82:83]
	v_lshl_add_u64 v[90:91], v[144:145], 1, v[82:83]
	s_waitcnt vmcnt(15)
	v_lshlrev_b32_e32 v92, 16, v192
	v_and_b32_e32 v93, 0xffff0000, v192
	v_lshlrev_b32_e32 v82, 16, v193
	v_and_b32_e32 v83, 0xffff0000, v193
	s_waitcnt vmcnt(14)
	v_lshlrev_b32_e32 v96, 16, v196
	v_and_b32_e32 v97, 0xffff0000, v196
	v_lshlrev_b32_e32 v86, 16, v197
	v_and_b32_e32 v87, 0xffff0000, v197
	v_lshlrev_b32_e32 v94, 16, v194
	v_and_b32_e32 v95, 0xffff0000, v194
	v_lshlrev_b32_e32 v84, 16, v195
	v_and_b32_e32 v85, 0xffff0000, v195
	v_lshlrev_b32_e32 v98, 16, v198
	v_and_b32_e32 v99, 0xffff0000, v198
	v_lshlrev_b32_e32 v88, 16, v199
	v_and_b32_e32 v89, 0xffff0000, v199
	v_pk_add_f32 v[78:79], v[78:79], v[82:83]
	v_pk_add_f32 v[76:77], v[76:77], v[92:93]
	v_pk_add_f32 v[70:71], v[70:71], v[86:87]
	v_pk_add_f32 v[68:69], v[68:69], v[96:97]
	v_pk_add_f32 v[74:75], v[74:75], v[84:85]
	v_pk_add_f32 v[72:73], v[72:73], v[94:95]
	v_pk_add_f32 v[82:83], v[66:67], v[88:89]
	v_pk_add_f32 v[84:85], v[64:65], v[98:99]
	v_mul_f32_e32 v66, v77, v77
	v_mul_f32_e32 v67, v79, v79
	v_mul_f32_e32 v86, v69, v69
	v_mul_f32_e32 v87, v71, v71
	v_cvt_pk_bf16_f32 v64, v76, v77
	v_mul_f32_e32 v77, v73, v73
	v_mul_f32_e32 v88, v85, v85
	v_fmac_f32_e32 v66, v76, v76
	v_fmac_f32_e32 v67, v78, v78
	v_fmac_f32_e32 v86, v68, v68
	v_fmac_f32_e32 v87, v70, v70
	v_cvt_pk_bf16_f32 v65, v78, v79
	v_mul_f32_e32 v79, v75, v75
	v_mul_f32_e32 v89, v83, v83
	v_fmac_f32_e32 v77, v72, v72
	v_fmac_f32_e32 v88, v84, v84
	v_add_f32_e32 v66, v66, v67
	v_add_f32_e32 v67, v86, v87
	v_fmac_f32_e32 v79, v74, v74
	v_fmac_f32_e32 v89, v82, v82
	v_add_f32_e32 v66, v77, v66
	v_add_f32_e32 v67, v88, v67
	v_add_f32_e32 v66, v79, v66
	v_add_f32_e32 v67, v89, v67
	v_add_f32_e32 v76, v66, v67
	v_mov_b32_e32 v77, v76
	s_nop 1
	v_permlane16_swap_b32_e32 v77, v76
	v_cvt_pk_bf16_f32 v66, v72, v73
	v_cvt_pk_bf16_f32 v67, v74, v75
	global_store_dwordx4 v[90:91], v[64:67], off
	s_waitcnt lgkmcnt(0)
	s_nop 0
	v_add_f32_e32 v64, v76, v77
	v_mov_b32_e32 v65, v64
	s_nop 1
	v_permlane32_swap_b32_e32 v65, v64
	v_cvt_pk_bf16_f32 v66, v68, v69
	v_cvt_pk_bf16_f32 v67, v70, v71
	v_cvt_pk_bf16_f32 v68, v84, v85
	v_cvt_pk_bf16_f32 v69, v82, v83
	global_store_dwordx4 v[90:91], v[66:69], off offset:256
	s_and_saveexec_b64 s[30:31], s[4:5]
	s_cbranch_execz .LBB0_795
	v_lshlrev_b64 v[66:67], 6, v[80:81]
	v_lshl_add_u64 v[66:67], s[12:13], 0, v[66:67]
	v_lshl_add_u64 v[66:67], s[28:29], 2, v[66:67]
	s_lshl_b32 s8, s49, 2
	v_lshl_add_u64 v[66:67], v[66:67], 0, s[8:9]
	s_waitcnt lgkmcnt(0)
	v_add_f32_e32 v64, v64, v65
	global_store_dword v[66:67], v64, off
.LBB0_795:
	s_or_b64 exec, exec, s[30:31]
	v_add_u32_e32 v64, 0x80, v146
	s_waitcnt lgkmcnt(0)
	v_ashrrev_i32_e32 v65, 31, v64
	v_lshlrev_b64 v[66:67], 11, v[64:65]
	v_lshl_add_u64 v[66:67], s[10:11], 0, v[66:67]
	v_lshl_add_u64 v[74:75], v[144:145], 1, v[66:67]
	s_waitcnt vmcnt(15)
	v_lshlrev_b32_e32 v76, 16, v200
	v_and_b32_e32 v77, 0xffff0000, v200
	v_lshlrev_b32_e32 v66, 16, v201
	v_and_b32_e32 v67, 0xffff0000, v201
	s_waitcnt vmcnt(14)
	v_lshlrev_b32_e32 v80, 16, v204
	v_and_b32_e32 v81, 0xffff0000, v204
	v_lshlrev_b32_e32 v70, 16, v205
	v_and_b32_e32 v71, 0xffff0000, v205
	v_lshlrev_b32_e32 v78, 16, v202
	v_and_b32_e32 v79, 0xffff0000, v202
	v_lshlrev_b32_e32 v68, 16, v203
	v_and_b32_e32 v69, 0xffff0000, v203
	v_lshlrev_b32_e32 v82, 16, v206
	v_and_b32_e32 v83, 0xffff0000, v206
	v_lshlrev_b32_e32 v72, 16, v207
	v_and_b32_e32 v73, 0xffff0000, v207
	v_pk_add_f32 v[62:63], v[62:63], v[66:67]
	v_pk_add_f32 v[60:61], v[60:61], v[76:77]
	v_pk_add_f32 v[54:55], v[54:55], v[70:71]
	v_pk_add_f32 v[52:53], v[52:53], v[80:81]
	v_pk_add_f32 v[58:59], v[58:59], v[68:69]
	v_pk_add_f32 v[56:57], v[56:57], v[78:79]
	v_pk_add_f32 v[66:67], v[50:51], v[72:73]
	v_pk_add_f32 v[68:69], v[48:49], v[82:83]
	v_mul_f32_e32 v50, v61, v61
	v_mul_f32_e32 v51, v63, v63
	v_mul_f32_e32 v70, v53, v53
	v_mul_f32_e32 v71, v55, v55
	v_cvt_pk_bf16_f32 v48, v60, v61
	v_mul_f32_e32 v61, v57, v57
	v_mul_f32_e32 v72, v69, v69
	v_fmac_f32_e32 v50, v60, v60
	v_fmac_f32_e32 v51, v62, v62
	v_fmac_f32_e32 v70, v52, v52
	v_fmac_f32_e32 v71, v54, v54
	v_cvt_pk_bf16_f32 v49, v62, v63
	v_mul_f32_e32 v63, v59, v59
	v_mul_f32_e32 v73, v67, v67
	v_fmac_f32_e32 v61, v56, v56
	v_fmac_f32_e32 v72, v68, v68
	v_add_f32_e32 v50, v50, v51
	v_add_f32_e32 v51, v70, v71
	v_fmac_f32_e32 v63, v58, v58
	v_fmac_f32_e32 v73, v66, v66
	v_add_f32_e32 v50, v61, v50
	v_add_f32_e32 v51, v72, v51
	v_add_f32_e32 v50, v63, v50
	v_add_f32_e32 v51, v73, v51
	v_add_f32_e32 v60, v50, v51
	v_mov_b32_e32 v61, v60
	s_nop 1
	v_permlane16_swap_b32_e32 v61, v60
	v_cvt_pk_bf16_f32 v50, v56, v57
	v_cvt_pk_bf16_f32 v51, v58, v59
	global_store_dwordx4 v[74:75], v[48:51], off
	s_waitcnt lgkmcnt(0)
	s_nop 0
	v_add_f32_e32 v48, v60, v61
	v_mov_b32_e32 v49, v48
	s_nop 1
	v_permlane32_swap_b32_e32 v49, v48
	v_cvt_pk_bf16_f32 v50, v52, v53
	v_cvt_pk_bf16_f32 v51, v54, v55
	v_cvt_pk_bf16_f32 v52, v68, v69
	v_cvt_pk_bf16_f32 v53, v66, v67
	global_store_dwordx4 v[74:75], v[50:53], off offset:256
	s_and_saveexec_b64 s[30:31], s[4:5]
	s_cbranch_execz .LBB0_797
	v_lshlrev_b64 v[50:51], 6, v[64:65]
	v_lshl_add_u64 v[50:51], s[12:13], 0, v[50:51]
	v_lshl_add_u64 v[50:51], s[28:29], 2, v[50:51]
	s_lshl_b32 s8, s49, 2
	v_lshl_add_u64 v[50:51], v[50:51], 0, s[8:9]
	s_waitcnt lgkmcnt(0)
	v_add_f32_e32 v48, v48, v49
	global_store_dword v[50:51], v48, off
.LBB0_797:
	s_or_b64 exec, exec, s[30:31]
	v_add_u32_e32 v48, 0x90, v146
	s_waitcnt lgkmcnt(0)
	v_ashrrev_i32_e32 v49, 31, v48
	v_lshlrev_b64 v[50:51], 11, v[48:49]
	v_lshl_add_u64 v[50:51], s[10:11], 0, v[50:51]
	v_lshl_add_u64 v[58:59], v[144:145], 1, v[50:51]
	s_waitcnt vmcnt(15)
	v_lshlrev_b32_e32 v60, 16, v208
	v_and_b32_e32 v61, 0xffff0000, v208
	v_lshlrev_b32_e32 v50, 16, v209
	v_and_b32_e32 v51, 0xffff0000, v209
	s_waitcnt vmcnt(14)
	v_lshlrev_b32_e32 v64, 16, v212
	v_and_b32_e32 v65, 0xffff0000, v212
	v_lshlrev_b32_e32 v54, 16, v213
	v_and_b32_e32 v55, 0xffff0000, v213
	v_lshlrev_b32_e32 v62, 16, v210
	v_and_b32_e32 v63, 0xffff0000, v210
	v_lshlrev_b32_e32 v52, 16, v211
	v_and_b32_e32 v53, 0xffff0000, v211
	v_lshlrev_b32_e32 v66, 16, v214
	v_and_b32_e32 v67, 0xffff0000, v214
	v_lshlrev_b32_e32 v56, 16, v215
	v_and_b32_e32 v57, 0xffff0000, v215
	v_pk_add_f32 v[46:47], v[46:47], v[50:51]
	v_pk_add_f32 v[44:45], v[44:45], v[60:61]
	v_pk_add_f32 v[38:39], v[38:39], v[54:55]
	v_pk_add_f32 v[36:37], v[36:37], v[64:65]
	v_pk_add_f32 v[42:43], v[42:43], v[52:53]
	v_pk_add_f32 v[40:41], v[40:41], v[62:63]
	v_pk_add_f32 v[50:51], v[34:35], v[56:57]
	v_pk_add_f32 v[52:53], v[32:33], v[66:67]
	v_mul_f32_e32 v34, v45, v45
	v_mul_f32_e32 v35, v47, v47
	v_mul_f32_e32 v54, v37, v37
	v_mul_f32_e32 v55, v39, v39
	v_cvt_pk_bf16_f32 v32, v44, v45
	v_mul_f32_e32 v45, v41, v41
	v_mul_f32_e32 v56, v53, v53
	v_fmac_f32_e32 v34, v44, v44
	v_fmac_f32_e32 v35, v46, v46
	v_fmac_f32_e32 v54, v36, v36
	v_fmac_f32_e32 v55, v38, v38
	v_cvt_pk_bf16_f32 v33, v46, v47
	v_mul_f32_e32 v47, v43, v43
	v_mul_f32_e32 v57, v51, v51
	v_fmac_f32_e32 v45, v40, v40
	v_fmac_f32_e32 v56, v52, v52
	v_add_f32_e32 v34, v34, v35
	v_add_f32_e32 v35, v54, v55
	v_fmac_f32_e32 v47, v42, v42
	v_fmac_f32_e32 v57, v50, v50
	v_add_f32_e32 v34, v45, v34
	v_add_f32_e32 v35, v56, v35
	v_add_f32_e32 v34, v47, v34
	v_add_f32_e32 v35, v57, v35
	v_add_f32_e32 v44, v34, v35
	v_mov_b32_e32 v45, v44
	s_nop 1
	v_permlane16_swap_b32_e32 v45, v44
	v_cvt_pk_bf16_f32 v34, v40, v41
	v_cvt_pk_bf16_f32 v35, v42, v43
	global_store_dwordx4 v[58:59], v[32:35], off
	s_waitcnt lgkmcnt(0)
	s_nop 0
	v_add_f32_e32 v32, v44, v45
	v_mov_b32_e32 v33, v32
	s_nop 1
	v_permlane32_swap_b32_e32 v33, v32
	v_cvt_pk_bf16_f32 v34, v36, v37
	v_cvt_pk_bf16_f32 v35, v38, v39
	v_cvt_pk_bf16_f32 v36, v52, v53
	v_cvt_pk_bf16_f32 v37, v50, v51
	global_store_dwordx4 v[58:59], v[34:37], off offset:256
	s_and_saveexec_b64 s[30:31], s[4:5]
	s_cbranch_execz .LBB0_799
	v_lshlrev_b64 v[34:35], 6, v[48:49]
	v_lshl_add_u64 v[34:35], s[12:13], 0, v[34:35]
	v_lshl_add_u64 v[34:35], s[28:29], 2, v[34:35]
	s_lshl_b32 s8, s49, 2
	v_lshl_add_u64 v[34:35], v[34:35], 0, s[8:9]
	s_waitcnt lgkmcnt(0)
	v_add_f32_e32 v32, v32, v33
	global_store_dword v[34:35], v32, off
.LBB0_799:
	s_or_b64 exec, exec, s[30:31]
	v_add_u32_e32 v32, 0xa0, v146
	s_waitcnt lgkmcnt(0)
	v_ashrrev_i32_e32 v33, 31, v32
	v_lshlrev_b64 v[34:35], 11, v[32:33]
	v_lshl_add_u64 v[34:35], s[10:11], 0, v[34:35]
	v_lshl_add_u64 v[42:43], v[144:145], 1, v[34:35]
	s_waitcnt vmcnt(15)
	v_lshlrev_b32_e32 v44, 16, v216
	v_and_b32_e32 v45, 0xffff0000, v216
	v_lshlrev_b32_e32 v34, 16, v217
	v_and_b32_e32 v35, 0xffff0000, v217
	s_waitcnt vmcnt(14)
	v_lshlrev_b32_e32 v48, 16, v220
	v_and_b32_e32 v49, 0xffff0000, v220
	v_lshlrev_b32_e32 v38, 16, v221
	v_and_b32_e32 v39, 0xffff0000, v221
	v_lshlrev_b32_e32 v46, 16, v218
	v_and_b32_e32 v47, 0xffff0000, v218
	v_lshlrev_b32_e32 v36, 16, v219
	v_and_b32_e32 v37, 0xffff0000, v219
	v_lshlrev_b32_e32 v50, 16, v222
	v_and_b32_e32 v51, 0xffff0000, v222
	v_lshlrev_b32_e32 v40, 16, v223
	v_and_b32_e32 v41, 0xffff0000, v223
	v_pk_add_f32 v[30:31], v[30:31], v[34:35]
	v_pk_add_f32 v[28:29], v[28:29], v[44:45]
	v_pk_add_f32 v[22:23], v[22:23], v[38:39]
	v_pk_add_f32 v[20:21], v[20:21], v[48:49]
	v_pk_add_f32 v[26:27], v[26:27], v[36:37]
	v_pk_add_f32 v[24:25], v[24:25], v[46:47]
	v_pk_add_f32 v[34:35], v[18:19], v[40:41]
	v_pk_add_f32 v[36:37], v[16:17], v[50:51]
	v_mul_f32_e32 v18, v29, v29
	v_mul_f32_e32 v19, v31, v31
	v_mul_f32_e32 v38, v21, v21
	v_mul_f32_e32 v39, v23, v23
	v_cvt_pk_bf16_f32 v16, v28, v29
	v_mul_f32_e32 v29, v25, v25
	v_mul_f32_e32 v40, v37, v37
	v_fmac_f32_e32 v18, v28, v28
	v_fmac_f32_e32 v19, v30, v30
	v_fmac_f32_e32 v38, v20, v20
	v_fmac_f32_e32 v39, v22, v22
	v_cvt_pk_bf16_f32 v17, v30, v31
	v_mul_f32_e32 v31, v27, v27
	v_mul_f32_e32 v41, v35, v35
	v_fmac_f32_e32 v29, v24, v24
	v_fmac_f32_e32 v40, v36, v36
	v_add_f32_e32 v18, v18, v19
	v_add_f32_e32 v19, v38, v39
	v_fmac_f32_e32 v31, v26, v26
	v_fmac_f32_e32 v41, v34, v34
	v_add_f32_e32 v18, v29, v18
	v_add_f32_e32 v19, v40, v19
	v_add_f32_e32 v18, v31, v18
	v_add_f32_e32 v19, v41, v19
	v_add_f32_e32 v28, v18, v19
	v_mov_b32_e32 v29, v28
	s_nop 1
	v_permlane16_swap_b32_e32 v29, v28
	v_cvt_pk_bf16_f32 v18, v24, v25
	v_cvt_pk_bf16_f32 v19, v26, v27
	global_store_dwordx4 v[42:43], v[16:19], off
	s_waitcnt lgkmcnt(0)
	s_nop 0
	v_add_f32_e32 v16, v28, v29
	v_mov_b32_e32 v17, v16
	s_nop 1
	v_permlane32_swap_b32_e32 v17, v16
	v_cvt_pk_bf16_f32 v18, v20, v21
	v_cvt_pk_bf16_f32 v19, v22, v23
	v_cvt_pk_bf16_f32 v20, v36, v37
	v_cvt_pk_bf16_f32 v21, v34, v35
	global_store_dwordx4 v[42:43], v[18:21], off offset:256
	s_and_saveexec_b64 s[30:31], s[4:5]
	s_cbranch_execz .LBB0_801
	v_lshlrev_b64 v[18:19], 6, v[32:33]
	v_lshl_add_u64 v[18:19], s[12:13], 0, v[18:19]
	v_lshl_add_u64 v[18:19], s[28:29], 2, v[18:19]
	s_lshl_b32 s8, s49, 2
	v_lshl_add_u64 v[18:19], v[18:19], 0, s[8:9]
	s_waitcnt lgkmcnt(0)
	v_add_f32_e32 v16, v16, v17
	global_store_dword v[18:19], v16, off
.LBB0_801:
	s_or_b64 exec, exec, s[30:31]
	v_add_u32_e32 v16, 0xb0, v146
	s_waitcnt lgkmcnt(0)
	v_ashrrev_i32_e32 v17, 31, v16
	v_lshlrev_b64 v[18:19], 11, v[16:17]
	v_lshl_add_u64 v[18:19], s[10:11], 0, v[18:19]
	v_lshl_add_u64 v[26:27], v[144:145], 1, v[18:19]
	s_waitcnt vmcnt(15)
	v_lshlrev_b32_e32 v28, 16, v224
	v_and_b32_e32 v29, 0xffff0000, v224
	v_lshlrev_b32_e32 v18, 16, v225
	v_and_b32_e32 v19, 0xffff0000, v225
	s_waitcnt vmcnt(14)
	v_lshlrev_b32_e32 v32, 16, v228
	v_and_b32_e32 v33, 0xffff0000, v228
	v_lshlrev_b32_e32 v22, 16, v229
	v_and_b32_e32 v23, 0xffff0000, v229
	v_lshlrev_b32_e32 v30, 16, v226
	v_and_b32_e32 v31, 0xffff0000, v226
	v_lshlrev_b32_e32 v20, 16, v227
	v_and_b32_e32 v21, 0xffff0000, v227
	v_lshlrev_b32_e32 v34, 16, v230
	v_and_b32_e32 v35, 0xffff0000, v230
	v_lshlrev_b32_e32 v24, 16, v231
	v_and_b32_e32 v25, 0xffff0000, v231
	v_pk_add_f32 v[14:15], v[14:15], v[18:19]
	v_pk_add_f32 v[12:13], v[12:13], v[28:29]
	v_pk_add_f32 v[6:7], v[6:7], v[22:23]
	v_pk_add_f32 v[4:5], v[4:5], v[32:33]
	v_pk_add_f32 v[10:11], v[10:11], v[20:21]
	v_pk_add_f32 v[8:9], v[8:9], v[30:31]
	v_pk_add_f32 v[18:19], v[2:3], v[24:25]
	v_pk_add_f32 v[20:21], v[0:1], v[34:35]
	v_mul_f32_e32 v2, v13, v13
	v_mul_f32_e32 v3, v15, v15
	v_mul_f32_e32 v22, v5, v5
	v_mul_f32_e32 v23, v7, v7
	v_cvt_pk_bf16_f32 v0, v12, v13
	v_mul_f32_e32 v13, v9, v9
	v_mul_f32_e32 v24, v21, v21
	v_fmac_f32_e32 v2, v12, v12
	v_fmac_f32_e32 v3, v14, v14
	v_fmac_f32_e32 v22, v4, v4
	v_fmac_f32_e32 v23, v6, v6
	v_cvt_pk_bf16_f32 v1, v14, v15
	v_mul_f32_e32 v15, v11, v11
	v_mul_f32_e32 v25, v19, v19
	v_fmac_f32_e32 v13, v8, v8
	v_fmac_f32_e32 v24, v20, v20
	v_add_f32_e32 v2, v2, v3
	v_add_f32_e32 v3, v22, v23
	v_fmac_f32_e32 v15, v10, v10
	v_fmac_f32_e32 v25, v18, v18
	v_add_f32_e32 v2, v13, v2
	v_add_f32_e32 v3, v24, v3
	v_add_f32_e32 v2, v15, v2
	v_add_f32_e32 v3, v25, v3
	v_add_f32_e32 v12, v2, v3
	v_mov_b32_e32 v13, v12
	s_nop 1
	v_permlane16_swap_b32_e32 v13, v12
	v_cvt_pk_bf16_f32 v2, v8, v9
	v_cvt_pk_bf16_f32 v3, v10, v11
	global_store_dwordx4 v[26:27], v[0:3], off
	s_waitcnt lgkmcnt(0)
	s_nop 0
	v_add_f32_e32 v0, v12, v13
	v_mov_b32_e32 v1, v0
	s_nop 1
	v_permlane32_swap_b32_e32 v1, v0
	v_cvt_pk_bf16_f32 v2, v4, v5
	v_cvt_pk_bf16_f32 v3, v6, v7
	v_cvt_pk_bf16_f32 v4, v20, v21
	v_cvt_pk_bf16_f32 v5, v18, v19
	global_store_dwordx4 v[26:27], v[2:5], off offset:256
	s_and_saveexec_b64 s[30:31], s[4:5]
	s_cbranch_execz .LBB0_782
	v_lshlrev_b64 v[2:3], 6, v[16:17]
	v_lshl_add_u64 v[2:3], s[12:13], 0, v[2:3]
	v_lshl_add_u64 v[2:3], s[28:29], 2, v[2:3]
	s_lshl_b32 s8, s49, 2
	v_lshl_add_u64 v[2:3], v[2:3], 0, s[8:9]
	s_waitcnt lgkmcnt(0)
	v_add_f32_e32 v0, v0, v1
	global_store_dword v[2:3], v0, off
	s_branch .LBB0_782

.LBB0_965:
	v_pk_add_f32 v[18:19], v[18:19], v[20:21]
	v_lshlrev_b64 v[16:17], 12, v[16:17]
	v_add_f32_e32 v18, v18, v19
	v_mov_b32_e32 v19, v18
	s_nop 1
	v_permlane16_swap_b32_e32 v19, v18
	v_lshl_add_u64 v[16:17], s[8:9], 0, v[16:17]
	v_lshl_add_u64 v[16:17], v[146:147], 2, v[16:17]
	s_mov_b32 s10, s51
	s_mov_b32 s53, s52
	s_waitcnt lgkmcnt(0)
	v_add_f32_e32 v18, v18, v19
	v_mov_b32_e32 v19, v18
	s_nop 1
	v_permlane32_swap_b32_e32 v19, v18
	s_mov_b64 s[22:23], s[6:7]
	s_mov_b64 s[20:21], s[4:5]
	s_waitcnt lgkmcnt(0)
	v_add_f32_e32 v18, v18, v19
	v_fmamk_f32 v18, v18, 0x3a800000, v207
	v_mul_f32_e32 v19, 0x4b800000, v18
	v_cmp_gt_f32_e32 vcc, s49, v18
	s_nop 1
	v_cndmask_b32_e32 v18, v18, v19, vcc
	v_rsq_f32_e32 v18, v18
	s_nop 0
	v_mul_f32_e32 v19, 0x45800000, v18
	v_cndmask_b32_e32 v18, v18, v19, vcc
	v_pk_mul_f32 v[20:21], v[178:179], v[18:19] op_sel_hi:[1,0]
	v_pk_mul_f32 v[22:23], v[176:177], v[18:19] op_sel_hi:[1,0]
	v_pk_mul_f32 v[24:25], v[174:175], v[18:19] op_sel_hi:[1,0]
	v_pk_mul_f32 v[28:29], v[170:171], v[18:19] op_sel_hi:[1,0]
	v_pk_mul_f32 v[14:15], v[14:15], v[22:23]
	v_pk_mul_f32 v[12:13], v[12:13], v[20:21]
	v_pk_mul_f32 v[10:11], v[10:11], v[28:29]
	v_pk_mul_f32 v[8:9], v[8:9], v[24:25]
	global_store_dwordx4 v[16:17], v[12:15], off nt
	global_store_dwordx4 v[16:17], v[8:11], off offset:16 nt
	s_and_b64 vcc, exec, s[2:3]
	s_nop 0
	v_pk_mul_f32 v[8:9], v[166:167], v[18:19] op_sel_hi:[1,0]
	v_pk_mul_f32 v[10:11], v[30:31], v[18:19] op_sel_hi:[1,0]
	v_pk_mul_f32 v[4:5], v[4:5], v[8:9]
	v_pk_mul_f32 v[6:7], v[6:7], v[10:11]
	global_store_dwordx4 v[16:17], v[4:7], off offset:512 nt
	s_nop 1
	v_pk_mul_f32 v[4:5], v[162:163], v[18:19] op_sel_hi:[1,0]
	v_pk_mul_f32 v[6:7], v[26:27], v[18:19] op_sel_hi:[1,0]
	v_pk_mul_f32 v[0:1], v[0:1], v[4:5]
	v_pk_mul_f32 v[2:3], v[2:3], v[6:7]
	global_store_dwordx4 v[16:17], v[0:3], off offset:528 nt
	s_cbranch_vccnz .LBB0_1038

.Lg973_nox:
	v_lshl_add_u32 v148, s53, 8, v200
	v_ashrrev_i32_e32 v149, 31, v148
	v_lshl_or_b32 v146, s10, 8, v202
	v_lshlrev_b64 v[150:151], 11, v[148:149]
	v_ashrrev_i32_e32 v147, 31, v146
	v_lshl_add_u64 v[150:151], s[12:13], 0, v[150:151]
	v_lshl_add_u64 v[154:155], v[146:147], 1, v[150:151]
	global_load_dwordx4 v[150:153], v[154:155], off
	s_nop 0
	global_load_dwordx4 v[154:157], v[154:155], off offset:256
	v_and_b32_e32 v159, 64, v206
	v_xor_b32_e32 v158, 16, v206
	v_add_u32_e32 v166, 64, v159
	v_cmp_lt_i32_e32 vcc, v158, v166
	s_lshl_b32 s20, s10, 2
	s_ashr_i32 s21, s20, 31
	v_cndmask_b32_e32 v158, v206, v158, vcc
	v_lshlrev_b32_e32 v208, 2, v158
	v_lshlrev_b64 v[182:183], 6, v[148:149]
	s_waitcnt vmcnt(0)
	v_lshlrev_b32_e32 v158, 16, v150
	v_and_b32_e32 v159, 0xffff0000, v150
	v_lshlrev_b32_e32 v150, 16, v151
	v_and_b32_e32 v151, 0xffff0000, v151
	v_lshlrev_b32_e32 v160, 16, v152
	v_and_b32_e32 v161, 0xffff0000, v152
	v_lshlrev_b32_e32 v162, 16, v154
	v_and_b32_e32 v163, 0xffff0000, v154
	v_lshlrev_b32_e32 v154, 16, v155
	v_and_b32_e32 v155, 0xffff0000, v155
	v_lshlrev_b32_e32 v164, 16, v156
	v_and_b32_e32 v165, 0xffff0000, v156
	v_pk_fma_f32 v[126:127], v[126:127], 0.5, v[150:151] op_sel_hi:[1,0,1]
	v_pk_fma_f32 v[150:151], v[124:125], 0.5, v[158:159] op_sel_hi:[1,0,1]
	v_pk_fma_f32 v[124:125], v[120:121], 0.5, v[160:161] op_sel_hi:[1,0,1]
	v_pk_fma_f32 v[118:119], v[118:119], 0.5, v[154:155] op_sel_hi:[1,0,1]
	v_pk_fma_f32 v[120:121], v[116:117], 0.5, v[162:163] op_sel_hi:[1,0,1]
	v_lshlrev_b32_e32 v152, 16, v153
	v_and_b32_e32 v153, 0xffff0000, v153
	v_lshlrev_b32_e32 v156, 16, v157
	v_and_b32_e32 v157, 0xffff0000, v157
	v_pk_fma_f32 v[116:117], v[112:113], 0.5, v[164:165] op_sel_hi:[1,0,1]
	v_mul_f32_e32 v112, v151, v151
	v_mul_f32_e32 v113, v127, v127
	v_mul_f32_e32 v154, v121, v121
	v_mul_f32_e32 v155, v119, v119
	v_pk_fma_f32 v[122:123], v[122:123], 0.5, v[152:153] op_sel_hi:[1,0,1]
	v_pk_fma_f32 v[114:115], v[114:115], 0.5, v[156:157] op_sel_hi:[1,0,1]
	v_mul_f32_e32 v152, v125, v125
	v_mul_f32_e32 v156, v117, v117
	v_fmac_f32_e32 v112, v150, v150
	v_fmac_f32_e32 v113, v126, v126
	v_fmac_f32_e32 v154, v120, v120
	v_fmac_f32_e32 v155, v118, v118
	v_mul_f32_e32 v153, v123, v123
	v_mul_f32_e32 v157, v115, v115
	v_fmac_f32_e32 v152, v124, v124
	v_fmac_f32_e32 v156, v116, v116
	v_add_f32_e32 v112, v112, v113
	v_add_f32_e32 v113, v154, v155
	v_fmac_f32_e32 v153, v122, v122
	v_fmac_f32_e32 v157, v114, v114
	v_add_f32_e32 v112, v152, v112
	v_add_f32_e32 v113, v156, v113
	v_add_f32_e32 v112, v153, v112
	v_add_f32_e32 v113, v157, v113
	v_add_f32_e32 v112, v112, v113
	v_mov_b32_e32 v113, v112
	s_nop 1
	v_permlane16_swap_b32_e32 v113, v112
	v_xor_b32_e32 v152, 32, v206
	v_cmp_lt_i32_e32 vcc, v152, v166
	s_waitcnt lgkmcnt(0)
	v_add_f32_e32 v112, v112, v113
	v_cndmask_b32_e32 v152, v206, v152, vcc
	v_lshlrev_b32_e32 v209, 2, v152
	v_mov_b32_e32 v113, v112
	s_nop 1
	v_permlane32_swap_b32_e32 v113, v112
	s_and_saveexec_b64 s[22:23], s[0:1]
	s_cbranch_execz .LBB0_976
	s_waitcnt lgkmcnt(0)
	v_add_f32_e32 v152, v112, v113
	v_lshl_add_u64 v[112:113], s[14:15], 0, v[182:183]
	v_lshl_add_u64 v[112:113], s[20:21], 2, v[112:113]
	s_lshl_b32 s10, s41, 2
	v_lshl_add_u64 v[112:113], v[112:113], 0, s[10:11]
	global_store_dword v[112:113], v152, off sc1
.LBB0_976:
	s_or_b64 exec, exec, s[22:23]
	v_or_b32_e32 v112, 16, v148
	s_waitcnt lgkmcnt(0)
	v_ashrrev_i32_e32 v113, 31, v112
	v_lshlrev_b64 v[152:153], 11, v[112:113]
	v_lshl_add_u64 v[152:153], s[12:13], 0, v[152:153]
	v_lshl_add_u64 v[156:157], v[146:147], 1, v[152:153]
	global_load_dwordx4 v[152:155], v[156:157], off
	s_nop 0
	global_load_dwordx4 v[156:159], v[156:157], off offset:256
	v_lshlrev_b64 v[180:181], 6, v[112:113]
	s_waitcnt vmcnt(1)
	v_lshlrev_b32_e32 v160, 16, v152
	v_and_b32_e32 v161, 0xffff0000, v152
	v_lshlrev_b32_e32 v152, 16, v153
	v_and_b32_e32 v153, 0xffff0000, v153
	v_lshlrev_b32_e32 v162, 16, v154
	v_and_b32_e32 v163, 0xffff0000, v154
	s_waitcnt vmcnt(0)
	v_lshlrev_b32_e32 v164, 16, v156
	v_and_b32_e32 v165, 0xffff0000, v156
	v_lshlrev_b32_e32 v156, 16, v157
	v_and_b32_e32 v157, 0xffff0000, v157
	v_lshlrev_b32_e32 v166, 16, v158
	v_and_b32_e32 v167, 0xffff0000, v158
	v_pk_fma_f32 v[110:111], v[110:111], 0.5, v[152:153] op_sel_hi:[1,0,1]
	v_pk_fma_f32 v[152:153], v[108:109], 0.5, v[160:161] op_sel_hi:[1,0,1]
	v_pk_fma_f32 v[108:109], v[104:105], 0.5, v[162:163] op_sel_hi:[1,0,1]
	v_pk_fma_f32 v[102:103], v[102:103], 0.5, v[156:157] op_sel_hi:[1,0,1]
	v_pk_fma_f32 v[104:105], v[100:101], 0.5, v[164:165] op_sel_hi:[1,0,1]
	v_lshlrev_b32_e32 v154, 16, v155
	v_and_b32_e32 v155, 0xffff0000, v155
	v_lshlrev_b32_e32 v158, 16, v159
	v_and_b32_e32 v159, 0xffff0000, v159
	v_pk_fma_f32 v[100:101], v[96:97], 0.5, v[166:167] op_sel_hi:[1,0,1]
	v_mul_f32_e32 v96, v153, v153
	v_mul_f32_e32 v97, v111, v111
	v_mul_f32_e32 v156, v105, v105
	v_mul_f32_e32 v157, v103, v103
	v_pk_fma_f32 v[106:107], v[106:107], 0.5, v[154:155] op_sel_hi:[1,0,1]
	v_pk_fma_f32 v[98:99], v[98:99], 0.5, v[158:159] op_sel_hi:[1,0,1]
	v_mul_f32_e32 v154, v109, v109
	v_mul_f32_e32 v158, v101, v101
	v_fmac_f32_e32 v96, v152, v152
	v_fmac_f32_e32 v97, v110, v110
	v_fmac_f32_e32 v156, v104, v104
	v_fmac_f32_e32 v157, v102, v102
	v_mul_f32_e32 v155, v107, v107
	v_mul_f32_e32 v159, v99, v99
	v_fmac_f32_e32 v154, v108, v108
	v_fmac_f32_e32 v158, v100, v100
	v_add_f32_e32 v96, v96, v97
	v_add_f32_e32 v97, v156, v157
	v_fmac_f32_e32 v155, v106, v106
	v_fmac_f32_e32 v159, v98, v98
	v_add_f32_e32 v96, v154, v96
	v_add_f32_e32 v97, v158, v97
	v_add_f32_e32 v96, v155, v96
	v_add_f32_e32 v97, v159, v97
	v_add_f32_e32 v96, v96, v97
	v_mov_b32_e32 v97, v96
	s_nop 1
	v_permlane16_swap_b32_e32 v97, v96
	s_waitcnt lgkmcnt(0)
	v_add_f32_e32 v96, v96, v97
	v_mov_b32_e32 v97, v96
	s_nop 1
	v_permlane32_swap_b32_e32 v97, v96
	s_and_saveexec_b64 s[22:23], s[0:1]
	s_cbranch_execz .LBB0_978
	s_waitcnt lgkmcnt(0)
	v_add_f32_e32 v154, v96, v97
	v_lshl_add_u64 v[96:97], s[14:15], 0, v[180:181]
	v_lshl_add_u64 v[96:97], s[20:21], 2, v[96:97]
	s_lshl_b32 s10, s41, 2
	v_lshl_add_u64 v[96:97], v[96:97], 0, s[10:11]
	global_store_dword v[96:97], v154, off sc1
.LBB0_978:
	s_or_b64 exec, exec, s[22:23]
	v_or_b32_e32 v96, 32, v148
	s_waitcnt lgkmcnt(0)
	v_ashrrev_i32_e32 v97, 31, v96
	v_lshlrev_b64 v[154:155], 11, v[96:97]
	v_lshl_add_u64 v[154:155], s[12:13], 0, v[154:155]
	v_lshl_add_u64 v[158:159], v[146:147], 1, v[154:155]
	global_load_dwordx4 v[154:157], v[158:159], off
	s_nop 0
	global_load_dwordx4 v[158:161], v[158:159], off offset:256
	v_lshlrev_b64 v[184:185], 6, v[96:97]
	s_waitcnt vmcnt(1)
	v_lshlrev_b32_e32 v162, 16, v154
	v_and_b32_e32 v163, 0xffff0000, v154
	v_lshlrev_b32_e32 v154, 16, v155
	v_and_b32_e32 v155, 0xffff0000, v155
	v_lshlrev_b32_e32 v164, 16, v156
	v_and_b32_e32 v165, 0xffff0000, v156
	s_waitcnt vmcnt(0)
	v_lshlrev_b32_e32 v166, 16, v158
	v_and_b32_e32 v167, 0xffff0000, v158
	v_lshlrev_b32_e32 v158, 16, v159
	v_and_b32_e32 v159, 0xffff0000, v159
	v_lshlrev_b32_e32 v168, 16, v160
	v_and_b32_e32 v169, 0xffff0000, v160
	v_pk_fma_f32 v[94:95], v[94:95], 0.5, v[154:155] op_sel_hi:[1,0,1]
	v_pk_fma_f32 v[154:155], v[92:93], 0.5, v[162:163] op_sel_hi:[1,0,1]
	v_pk_fma_f32 v[92:93], v[88:89], 0.5, v[164:165] op_sel_hi:[1,0,1]
	v_pk_fma_f32 v[86:87], v[86:87], 0.5, v[158:159] op_sel_hi:[1,0,1]
	v_pk_fma_f32 v[88:89], v[84:85], 0.5, v[166:167] op_sel_hi:[1,0,1]
	v_lshlrev_b32_e32 v156, 16, v157
	v_and_b32_e32 v157, 0xffff0000, v157
	v_lshlrev_b32_e32 v160, 16, v161
	v_and_b32_e32 v161, 0xffff0000, v161
	v_pk_fma_f32 v[84:85], v[80:81], 0.5, v[168:169] op_sel_hi:[1,0,1]
	v_mul_f32_e32 v80, v155, v155
	v_mul_f32_e32 v81, v95, v95
	v_mul_f32_e32 v158, v89, v89
	v_mul_f32_e32 v159, v87, v87
	v_pk_fma_f32 v[90:91], v[90:91], 0.5, v[156:157] op_sel_hi:[1,0,1]
	v_pk_fma_f32 v[82:83], v[82:83], 0.5, v[160:161] op_sel_hi:[1,0,1]
	v_mul_f32_e32 v156, v93, v93
	v_mul_f32_e32 v160, v85, v85
	v_fmac_f32_e32 v80, v154, v154
	v_fmac_f32_e32 v81, v94, v94
	v_fmac_f32_e32 v158, v88, v88
	v_fmac_f32_e32 v159, v86, v86
	v_mul_f32_e32 v157, v91, v91
	v_mul_f32_e32 v161, v83, v83
	v_fmac_f32_e32 v156, v92, v92
	v_fmac_f32_e32 v160, v84, v84
	v_add_f32_e32 v80, v80, v81
	v_add_f32_e32 v81, v158, v159
	v_fmac_f32_e32 v157, v90, v90
	v_fmac_f32_e32 v161, v82, v82
	v_add_f32_e32 v80, v156, v80
	v_add_f32_e32 v81, v160, v81
	v_add_f32_e32 v80, v157, v80
	v_add_f32_e32 v81, v161, v81
	v_add_f32_e32 v80, v80, v81
	v_mov_b32_e32 v81, v80
	s_nop 1
	v_permlane16_swap_b32_e32 v81, v80
	s_waitcnt lgkmcnt(0)
	v_add_f32_e32 v80, v80, v81
	v_mov_b32_e32 v81, v80
	s_nop 1
	v_permlane32_swap_b32_e32 v81, v80
	s_and_saveexec_b64 s[22:23], s[0:1]
	s_cbranch_execz .LBB0_980
	s_waitcnt lgkmcnt(0)
	v_add_f32_e32 v156, v80, v81
	v_lshl_add_u64 v[80:81], s[14:15], 0, v[184:185]
	v_lshl_add_u64 v[80:81], s[20:21], 2, v[80:81]
	s_lshl_b32 s10, s41, 2
	v_lshl_add_u64 v[80:81], v[80:81], 0, s[10:11]
	global_store_dword v[80:81], v156, off sc1
.LBB0_980:
	s_or_b64 exec, exec, s[22:23]
	v_or_b32_e32 v80, 48, v148
	s_waitcnt lgkmcnt(0)
	v_ashrrev_i32_e32 v81, 31, v80
	v_lshlrev_b64 v[156:157], 11, v[80:81]
	v_lshl_add_u64 v[156:157], s[12:13], 0, v[156:157]
	v_lshl_add_u64 v[160:161], v[146:147], 1, v[156:157]
	global_load_dwordx4 v[156:159], v[160:161], off
	s_nop 0
	global_load_dwordx4 v[160:163], v[160:161], off offset:256
	v_lshlrev_b64 v[186:187], 6, v[80:81]
	s_waitcnt vmcnt(1)
	v_lshlrev_b32_e32 v164, 16, v156
	v_and_b32_e32 v165, 0xffff0000, v156
	v_lshlrev_b32_e32 v156, 16, v157
	v_and_b32_e32 v157, 0xffff0000, v157
	v_lshlrev_b32_e32 v166, 16, v158
	v_and_b32_e32 v167, 0xffff0000, v158
	s_waitcnt vmcnt(0)
	v_lshlrev_b32_e32 v168, 16, v160
	v_and_b32_e32 v169, 0xffff0000, v160
	v_lshlrev_b32_e32 v160, 16, v161
	v_and_b32_e32 v161, 0xffff0000, v161
	v_lshlrev_b32_e32 v170, 16, v162
	v_and_b32_e32 v171, 0xffff0000, v162
	v_pk_fma_f32 v[78:79], v[78:79], 0.5, v[156:157] op_sel_hi:[1,0,1]
	v_pk_fma_f32 v[156:157], v[76:77], 0.5, v[164:165] op_sel_hi:[1,0,1]
	v_pk_fma_f32 v[76:77], v[72:73], 0.5, v[166:167] op_sel_hi:[1,0,1]
	v_pk_fma_f32 v[70:71], v[70:71], 0.5, v[160:161] op_sel_hi:[1,0,1]
	v_pk_fma_f32 v[72:73], v[68:69], 0.5, v[168:169] op_sel_hi:[1,0,1]
	v_lshlrev_b32_e32 v158, 16, v159
	v_and_b32_e32 v159, 0xffff0000, v159
	v_lshlrev_b32_e32 v162, 16, v163
	v_and_b32_e32 v163, 0xffff0000, v163
	v_pk_fma_f32 v[68:69], v[64:65], 0.5, v[170:171] op_sel_hi:[1,0,1]
	v_mul_f32_e32 v64, v157, v157
	v_mul_f32_e32 v65, v79, v79
	v_mul_f32_e32 v160, v73, v73
	v_mul_f32_e32 v161, v71, v71
	v_pk_fma_f32 v[74:75], v[74:75], 0.5, v[158:159] op_sel_hi:[1,0,1]
	v_pk_fma_f32 v[66:67], v[66:67], 0.5, v[162:163] op_sel_hi:[1,0,1]
	v_mul_f32_e32 v158, v77, v77
	v_mul_f32_e32 v162, v69, v69
	v_fmac_f32_e32 v64, v156, v156
	v_fmac_f32_e32 v65, v78, v78
	v_fmac_f32_e32 v160, v72, v72
	v_fmac_f32_e32 v161, v70, v70
	v_mul_f32_e32 v159, v75, v75
	v_mul_f32_e32 v163, v67, v67
	v_fmac_f32_e32 v158, v76, v76
	v_fmac_f32_e32 v162, v68, v68
	v_add_f32_e32 v64, v64, v65
	v_add_f32_e32 v65, v160, v161
	v_fmac_f32_e32 v159, v74, v74
	v_fmac_f32_e32 v163, v66, v66
	v_add_f32_e32 v64, v158, v64
	v_add_f32_e32 v65, v162, v65
	v_add_f32_e32 v64, v159, v64
	v_add_f32_e32 v65, v163, v65
	v_add_f32_e32 v64, v64, v65
	v_mov_b32_e32 v65, v64
	s_nop 1
	v_permlane16_swap_b32_e32 v65, v64
	s_waitcnt lgkmcnt(0)
	v_add_f32_e32 v64, v64, v65
	v_mov_b32_e32 v65, v64
	s_nop 1
	v_permlane32_swap_b32_e32 v65, v64
	s_and_saveexec_b64 s[22:23], s[0:1]
	s_cbranch_execz .LBB0_982
	s_waitcnt lgkmcnt(0)
	v_add_f32_e32 v158, v64, v65
	v_lshl_add_u64 v[64:65], s[14:15], 0, v[186:187]
	v_lshl_add_u64 v[64:65], s[20:21], 2, v[64:65]
	s_lshl_b32 s10, s41, 2
	v_lshl_add_u64 v[64:65], v[64:65], 0, s[10:11]
	global_store_dword v[64:65], v158, off sc1
.LBB0_982:
	s_or_b64 exec, exec, s[22:23]
	v_add_u32_e32 v64, 0x80, v148
	s_waitcnt lgkmcnt(0)
	v_ashrrev_i32_e32 v65, 31, v64
	v_lshlrev_b64 v[158:159], 11, v[64:65]
	v_lshl_add_u64 v[158:159], s[12:13], 0, v[158:159]
	v_lshl_add_u64 v[162:163], v[146:147], 1, v[158:159]
	global_load_dwordx4 v[158:161], v[162:163], off
	s_nop 0
	global_load_dwordx4 v[162:165], v[162:163], off offset:256
	v_lshlrev_b64 v[188:189], 6, v[64:65]
	s_waitcnt vmcnt(1)
	v_lshlrev_b32_e32 v166, 16, v158
	v_and_b32_e32 v167, 0xffff0000, v158
	v_lshlrev_b32_e32 v158, 16, v159
	v_and_b32_e32 v159, 0xffff0000, v159
	v_lshlrev_b32_e32 v168, 16, v160
	v_and_b32_e32 v169, 0xffff0000, v160
	s_waitcnt vmcnt(0)
	v_lshlrev_b32_e32 v170, 16, v162
	v_and_b32_e32 v171, 0xffff0000, v162
	v_lshlrev_b32_e32 v162, 16, v163
	v_and_b32_e32 v163, 0xffff0000, v163
	v_lshlrev_b32_e32 v172, 16, v164
	v_and_b32_e32 v173, 0xffff0000, v164
	v_pk_fma_f32 v[62:63], v[62:63], 0.5, v[158:159] op_sel_hi:[1,0,1]
	v_pk_fma_f32 v[158:159], v[60:61], 0.5, v[166:167] op_sel_hi:[1,0,1]
	v_pk_fma_f32 v[60:61], v[56:57], 0.5, v[168:169] op_sel_hi:[1,0,1]
	v_pk_fma_f32 v[54:55], v[54:55], 0.5, v[162:163] op_sel_hi:[1,0,1]
	v_pk_fma_f32 v[56:57], v[52:53], 0.5, v[170:171] op_sel_hi:[1,0,1]
	v_lshlrev_b32_e32 v160, 16, v161
	v_and_b32_e32 v161, 0xffff0000, v161
	v_lshlrev_b32_e32 v164, 16, v165
	v_and_b32_e32 v165, 0xffff0000, v165
	v_pk_fma_f32 v[52:53], v[48:49], 0.5, v[172:173] op_sel_hi:[1,0,1]
	v_mul_f32_e32 v48, v159, v159
	v_mul_f32_e32 v49, v63, v63
	v_mul_f32_e32 v162, v57, v57
	v_mul_f32_e32 v163, v55, v55
	v_pk_fma_f32 v[58:59], v[58:59], 0.5, v[160:161] op_sel_hi:[1,0,1]
	v_pk_fma_f32 v[50:51], v[50:51], 0.5, v[164:165] op_sel_hi:[1,0,1]
	v_mul_f32_e32 v160, v61, v61
	v_mul_f32_e32 v164, v53, v53
	v_fmac_f32_e32 v48, v158, v158
	v_fmac_f32_e32 v49, v62, v62
	v_fmac_f32_e32 v162, v56, v56
	v_fmac_f32_e32 v163, v54, v54
	v_mul_f32_e32 v161, v59, v59
	v_mul_f32_e32 v165, v51, v51
	v_fmac_f32_e32 v160, v60, v60
	v_fmac_f32_e32 v164, v52, v52
	v_add_f32_e32 v48, v48, v49
	v_add_f32_e32 v49, v162, v163
	v_fmac_f32_e32 v161, v58, v58
	v_fmac_f32_e32 v165, v50, v50
	v_add_f32_e32 v48, v160, v48
	v_add_f32_e32 v49, v164, v49
	v_add_f32_e32 v48, v161, v48
	v_add_f32_e32 v49, v165, v49
	v_add_f32_e32 v48, v48, v49
	v_mov_b32_e32 v49, v48
	s_nop 1
	v_permlane16_swap_b32_e32 v49, v48
	s_waitcnt lgkmcnt(0)
	v_add_f32_e32 v48, v48, v49
	v_mov_b32_e32 v49, v48
	s_nop 1
	v_permlane32_swap_b32_e32 v49, v48
	s_and_saveexec_b64 s[22:23], s[0:1]
	s_cbranch_execz .LBB0_984
	s_waitcnt lgkmcnt(0)
	v_add_f32_e32 v160, v48, v49
	v_lshl_add_u64 v[48:49], s[14:15], 0, v[188:189]
	v_lshl_add_u64 v[48:49], s[20:21], 2, v[48:49]
	s_lshl_b32 s10, s41, 2
	v_lshl_add_u64 v[48:49], v[48:49], 0, s[10:11]
	global_store_dword v[48:49], v160, off sc1
.LBB0_984:
	s_or_b64 exec, exec, s[22:23]
	v_add_u32_e32 v48, 0x90, v148
	s_waitcnt lgkmcnt(0)
	v_ashrrev_i32_e32 v49, 31, v48
	v_lshlrev_b64 v[160:161], 11, v[48:49]
	v_lshl_add_u64 v[160:161], s[12:13], 0, v[160:161]
	v_lshl_add_u64 v[164:165], v[146:147], 1, v[160:161]
	global_load_dwordx4 v[160:163], v[164:165], off
	s_nop 0
	global_load_dwordx4 v[164:167], v[164:165], off offset:256
	v_lshlrev_b64 v[190:191], 6, v[48:49]
	s_waitcnt vmcnt(1)
	v_lshlrev_b32_e32 v168, 16, v160
	v_and_b32_e32 v169, 0xffff0000, v160
	v_lshlrev_b32_e32 v160, 16, v161
	v_and_b32_e32 v161, 0xffff0000, v161
	v_lshlrev_b32_e32 v170, 16, v162
	v_and_b32_e32 v171, 0xffff0000, v162
	s_waitcnt vmcnt(0)
	v_lshlrev_b32_e32 v172, 16, v164
	v_and_b32_e32 v173, 0xffff0000, v164
	v_lshlrev_b32_e32 v164, 16, v165
	v_and_b32_e32 v165, 0xffff0000, v165
	v_lshlrev_b32_e32 v174, 16, v166
	v_and_b32_e32 v175, 0xffff0000, v166
	v_pk_fma_f32 v[46:47], v[46:47], 0.5, v[160:161] op_sel_hi:[1,0,1]
	v_pk_fma_f32 v[160:161], v[44:45], 0.5, v[168:169] op_sel_hi:[1,0,1]
	v_pk_fma_f32 v[44:45], v[40:41], 0.5, v[170:171] op_sel_hi:[1,0,1]
	v_pk_fma_f32 v[38:39], v[38:39], 0.5, v[164:165] op_sel_hi:[1,0,1]
	v_pk_fma_f32 v[40:41], v[36:37], 0.5, v[172:173] op_sel_hi:[1,0,1]
	v_lshlrev_b32_e32 v162, 16, v163
	v_and_b32_e32 v163, 0xffff0000, v163
	v_lshlrev_b32_e32 v166, 16, v167
	v_and_b32_e32 v167, 0xffff0000, v167
	v_pk_fma_f32 v[36:37], v[32:33], 0.5, v[174:175] op_sel_hi:[1,0,1]
	v_mul_f32_e32 v32, v161, v161
	v_mul_f32_e32 v33, v47, v47
	v_mul_f32_e32 v164, v41, v41
	v_mul_f32_e32 v165, v39, v39
	v_pk_fma_f32 v[42:43], v[42:43], 0.5, v[162:163] op_sel_hi:[1,0,1]
	v_pk_fma_f32 v[34:35], v[34:35], 0.5, v[166:167] op_sel_hi:[1,0,1]
	v_mul_f32_e32 v162, v45, v45
	v_mul_f32_e32 v166, v37, v37
	v_fmac_f32_e32 v32, v160, v160
	v_fmac_f32_e32 v33, v46, v46
	v_fmac_f32_e32 v164, v40, v40
	v_fmac_f32_e32 v165, v38, v38
	v_mul_f32_e32 v163, v43, v43
	v_mul_f32_e32 v167, v35, v35
	v_fmac_f32_e32 v162, v44, v44
	v_fmac_f32_e32 v166, v36, v36
	v_add_f32_e32 v32, v32, v33
	v_add_f32_e32 v33, v164, v165
	v_fmac_f32_e32 v163, v42, v42
	v_fmac_f32_e32 v167, v34, v34
	v_add_f32_e32 v32, v162, v32
	v_add_f32_e32 v33, v166, v33
	v_add_f32_e32 v32, v163, v32
	v_add_f32_e32 v33, v167, v33
	v_add_f32_e32 v32, v32, v33
	v_mov_b32_e32 v33, v32
	s_nop 1
	v_permlane16_swap_b32_e32 v33, v32
	s_waitcnt lgkmcnt(0)
	v_add_f32_e32 v32, v32, v33
	v_mov_b32_e32 v33, v32
	s_nop 1
	v_permlane32_swap_b32_e32 v33, v32
	s_and_saveexec_b64 s[22:23], s[0:1]
	s_cbranch_execz .LBB0_986
	s_waitcnt lgkmcnt(0)
	v_add_f32_e32 v162, v32, v33
	v_lshl_add_u64 v[32:33], s[14:15], 0, v[190:191]
	v_lshl_add_u64 v[32:33], s[20:21], 2, v[32:33]
	s_lshl_b32 s10, s41, 2
	v_lshl_add_u64 v[32:33], v[32:33], 0, s[10:11]
	global_store_dword v[32:33], v162, off sc1
.LBB0_986:
	s_or_b64 exec, exec, s[22:23]
	v_add_u32_e32 v32, 0xa0, v148
	s_waitcnt lgkmcnt(0)
	v_ashrrev_i32_e32 v33, 31, v32
	v_lshlrev_b64 v[162:163], 11, v[32:33]
	v_lshl_add_u64 v[162:163], s[12:13], 0, v[162:163]
	v_lshl_add_u64 v[166:167], v[146:147], 1, v[162:163]
	global_load_dwordx4 v[162:165], v[166:167], off
	s_nop 0
	global_load_dwordx4 v[166:169], v[166:167], off offset:256
	s_waitcnt vmcnt(1)
	v_lshlrev_b32_e32 v170, 16, v162
	v_and_b32_e32 v171, 0xffff0000, v162
	v_lshlrev_b32_e32 v162, 16, v163
	v_and_b32_e32 v163, 0xffff0000, v163
	v_lshlrev_b32_e32 v174, 16, v164
	v_and_b32_e32 v175, 0xffff0000, v164
	v_lshlrev_b32_e32 v164, 16, v165
	v_and_b32_e32 v165, 0xffff0000, v165
	s_waitcnt vmcnt(0)
	v_lshlrev_b32_e32 v176, 16, v166
	v_and_b32_e32 v177, 0xffff0000, v166
	v_lshlrev_b32_e32 v166, 16, v167
	v_and_b32_e32 v167, 0xffff0000, v167
	v_lshlrev_b32_e32 v178, 16, v168
	v_and_b32_e32 v179, 0xffff0000, v168
	v_lshlrev_b32_e32 v192, 16, v169
	v_and_b32_e32 v193, 0xffff0000, v169
	v_pk_fma_f32 v[168:169], v[30:31], 0.5, v[162:163] op_sel_hi:[1,0,1]
	v_pk_fma_f32 v[172:173], v[28:29], 0.5, v[170:171] op_sel_hi:[1,0,1]
	v_pk_fma_f32 v[28:29], v[26:27], 0.5, v[164:165] op_sel_hi:[1,0,1]
	v_pk_fma_f32 v[164:165], v[24:25], 0.5, v[174:175] op_sel_hi:[1,0,1]
	v_pk_fma_f32 v[22:23], v[22:23], 0.5, v[166:167] op_sel_hi:[1,0,1]
	v_pk_fma_f32 v[24:25], v[20:21], 0.5, v[176:177] op_sel_hi:[1,0,1]
	v_pk_fma_f32 v[20:21], v[16:17], 0.5, v[178:179] op_sel_hi:[1,0,1]
	v_mul_f32_e32 v16, v173, v173
	v_mul_f32_e32 v17, v169, v169
	v_mul_f32_e32 v30, v25, v25
	v_mul_f32_e32 v31, v23, v23
	v_pk_fma_f32 v[18:19], v[18:19], 0.5, v[192:193] op_sel_hi:[1,0,1]
	v_mul_f32_e32 v26, v165, v165
	v_mul_f32_e32 v162, v21, v21
	v_fmac_f32_e32 v16, v172, v172
	v_fmac_f32_e32 v17, v168, v168
	v_fmac_f32_e32 v30, v24, v24
	v_fmac_f32_e32 v31, v22, v22
	v_mul_f32_e32 v27, v29, v29
	v_mul_f32_e32 v163, v19, v19
	v_fmac_f32_e32 v26, v164, v164
	v_fmac_f32_e32 v162, v20, v20
	v_add_f32_e32 v16, v16, v17
	v_add_f32_e32 v17, v30, v31
	v_fmac_f32_e32 v27, v28, v28
	v_fmac_f32_e32 v163, v18, v18
	v_add_f32_e32 v16, v26, v16
	v_add_f32_e32 v17, v162, v17
	v_add_f32_e32 v16, v27, v16
	v_add_f32_e32 v17, v163, v17
	v_add_f32_e32 v16, v16, v17
	v_mov_b32_e32 v17, v16
	s_nop 1
	v_permlane16_swap_b32_e32 v17, v16
	v_lshlrev_b64 v[192:193], 6, v[32:33]
	s_waitcnt lgkmcnt(0)
	v_add_f32_e32 v16, v16, v17
	v_mov_b32_e32 v17, v16
	s_nop 1
	v_permlane32_swap_b32_e32 v17, v16
	s_and_saveexec_b64 s[22:23], s[0:1]
	s_cbranch_execz .LBB0_988
	s_waitcnt lgkmcnt(0)
	v_add_f32_e32 v26, v16, v17
	v_lshl_add_u64 v[16:17], s[14:15], 0, v[192:193]
	v_lshl_add_u64 v[16:17], s[20:21], 2, v[16:17]
	s_lshl_b32 s10, s41, 2
	v_lshl_add_u64 v[16:17], v[16:17], 0, s[10:11]
	global_store_dword v[16:17], v26, off sc1
.LBB0_988:
	s_or_b64 exec, exec, s[22:23]
	v_add_u32_e32 v16, 0xb0, v148
	s_waitcnt lgkmcnt(0)
	v_ashrrev_i32_e32 v17, 31, v16
	v_lshlrev_b64 v[26:27], 11, v[16:17]
	v_lshl_add_u64 v[26:27], s[12:13], 0, v[26:27]
	v_lshl_add_u64 v[26:27], v[146:147], 1, v[26:27]
	global_load_dwordx4 v[174:177], v[26:27], off
	global_load_dwordx4 v[194:197], v[26:27], off offset:256
	s_waitcnt vmcnt(1)
	v_lshlrev_b32_e32 v26, 16, v174
	v_and_b32_e32 v27, 0xffff0000, v174
	v_lshlrev_b32_e32 v30, 16, v175
	v_and_b32_e32 v31, 0xffff0000, v175
	v_lshlrev_b32_e32 v166, 16, v177
	v_and_b32_e32 v167, 0xffff0000, v177
	s_waitcnt vmcnt(0)
	v_lshlrev_b32_e32 v198, 16, v194
	v_and_b32_e32 v199, 0xffff0000, v194
	v_lshlrev_b32_e32 v194, 16, v195
	v_and_b32_e32 v195, 0xffff0000, v195
	v_lshlrev_b32_e32 v162, 16, v176
	v_and_b32_e32 v163, 0xffff0000, v176
	v_lshlrev_b32_e32 v210, 16, v196
	v_and_b32_e32 v211, 0xffff0000, v196
	v_pk_fma_f32 v[176:177], v[14:15], 0.5, v[30:31] op_sel_hi:[1,0,1]
	v_pk_fma_f32 v[178:179], v[12:13], 0.5, v[26:27] op_sel_hi:[1,0,1]
	v_pk_fma_f32 v[170:171], v[10:11], 0.5, v[166:167] op_sel_hi:[1,0,1]
	v_pk_fma_f32 v[30:31], v[6:7], 0.5, v[194:195] op_sel_hi:[1,0,1]
	v_pk_fma_f32 v[166:167], v[4:5], 0.5, v[198:199] op_sel_hi:[1,0,1]
	v_lshlrev_b32_e32 v196, 16, v197
	v_and_b32_e32 v197, 0xffff0000, v197
	v_pk_fma_f32 v[174:175], v[8:9], 0.5, v[162:163] op_sel_hi:[1,0,1]
	v_pk_fma_f32 v[162:163], v[0:1], 0.5, v[210:211] op_sel_hi:[1,0,1]
	v_mul_f32_e32 v0, v179, v179
	v_mul_f32_e32 v1, v177, v177
	v_mul_f32_e32 v4, v167, v167
	v_mul_f32_e32 v5, v31, v31
	v_pk_fma_f32 v[26:27], v[2:3], 0.5, v[196:197] op_sel_hi:[1,0,1]
	v_mul_f32_e32 v2, v175, v175
	v_mul_f32_e32 v6, v163, v163
	v_fmac_f32_e32 v0, v178, v178
	v_fmac_f32_e32 v1, v176, v176
	v_fmac_f32_e32 v4, v166, v166
	v_fmac_f32_e32 v5, v30, v30
	v_mul_f32_e32 v3, v171, v171
	v_mul_f32_e32 v7, v27, v27
	v_fmac_f32_e32 v2, v174, v174
	v_fmac_f32_e32 v6, v162, v162
	v_add_f32_e32 v0, v0, v1
	v_add_f32_e32 v1, v4, v5
	v_fmac_f32_e32 v3, v170, v170
	v_fmac_f32_e32 v7, v26, v26
	v_add_f32_e32 v0, v2, v0
	v_add_f32_e32 v1, v6, v1
	v_add_f32_e32 v0, v3, v0
	v_add_f32_e32 v1, v7, v1
	v_add_f32_e32 v0, v0, v1
	v_mov_b32_e32 v1, v0
	s_nop 1
	v_permlane16_swap_b32_e32 v1, v0
	v_lshlrev_b64 v[194:195], 6, v[16:17]
	s_waitcnt lgkmcnt(0)
	v_add_f32_e32 v0, v0, v1
	v_mov_b32_e32 v1, v0
	s_nop 1
	v_permlane32_swap_b32_e32 v1, v0
	s_and_saveexec_b64 s[22:23], s[0:1]
	s_cbranch_execz .LBB0_990
	s_waitcnt lgkmcnt(0)
	v_add_f32_e32 v2, v0, v1
	v_lshl_add_u64 v[0:1], s[14:15], 0, v[194:195]
	v_lshl_add_u64 v[0:1], s[20:21], 2, v[0:1]
	s_lshl_b32 s10, s41, 2
	v_lshl_add_u64 v[0:1], v[0:1], 0, s[10:11]
	global_store_dword v[0:1], v2, off sc1

.LBB0_996:
	v_pk_add_f32 v[182:183], v[182:183], v[196:197]
	v_lshlrev_b64 v[148:149], 12, v[148:149]
	v_add_f32_e32 v182, v182, v183
	v_mov_b32_e32 v183, v182
	s_nop 1
	v_permlane16_swap_b32_e32 v183, v182
	v_lshl_add_u64 v[148:149], s[8:9], 0, v[148:149]
	s_waitcnt lgkmcnt(0)
	v_add_f32_e32 v182, v182, v183
	v_mov_b32_e32 v183, v182
	s_nop 1
	v_permlane32_swap_b32_e32 v183, v182
	s_waitcnt lgkmcnt(0)
	v_add_f32_e32 v182, v182, v183
	v_fmamk_f32 v182, v182, 0x3a800000, v207
	v_mul_f32_e32 v183, 0x4b800000, v182
	v_cmp_gt_f32_e32 vcc, s49, v182
	s_nop 1
	v_cndmask_b32_e32 v182, v182, v183, vcc
	v_rsq_f32_e32 v196, v182
	v_lshl_add_u64 v[182:183], v[146:147], 2, v[148:149]
	v_mul_f32_e32 v148, 0x45800000, v196
	v_cndmask_b32_e32 v196, v196, v148, vcc
	v_pk_mul_f32 v[148:149], v[150:151], v[196:197] op_sel_hi:[1,0]
	v_pk_mul_f32 v[126:127], v[126:127], v[196:197] op_sel_hi:[1,0]
	v_pk_mul_f32 v[198:199], v[124:125], v[196:197] op_sel_hi:[1,0]
	v_pk_mul_f32 v[150:151], v[122:123], v[196:197] op_sel_hi:[1,0]
	v_pk_mul_f32 v[124:125], v[14:15], v[126:127]
	v_pk_mul_f32 v[122:123], v[12:13], v[148:149]
	v_pk_mul_f32 v[150:151], v[10:11], v[150:151]
	v_pk_mul_f32 v[148:149], v[8:9], v[198:199]
	global_store_dwordx4 v[182:183], v[122:125], off nt
	global_store_dwordx4 v[182:183], v[148:151], off offset:16 nt
	v_pk_mul_f32 v[118:119], v[118:119], v[196:197] op_sel_hi:[1,0]
	v_pk_mul_f32 v[122:123], v[120:121], v[196:197] op_sel_hi:[1,0]
	v_pk_mul_f32 v[120:121], v[6:7], v[118:119]
	v_pk_mul_f32 v[118:119], v[4:5], v[122:123]
	global_store_dwordx4 v[182:183], v[118:121], off offset:512 nt
	v_pk_mul_f32 v[114:115], v[114:115], v[196:197] op_sel_hi:[1,0]
	s_nop 0
	v_pk_mul_f32 v[118:119], v[116:117], v[196:197] op_sel_hi:[1,0]
	v_pk_mul_f32 v[116:117], v[2:3], v[114:115]
	v_pk_mul_f32 v[114:115], v[0:1], v[118:119]
	global_store_dwordx4 v[182:183], v[114:117], off offset:528 nt
	s_nop 1
	v_lshl_add_u64 v[114:115], v[136:137], 0, v[180:181]
	s_branch .LBB0_999

.LBB0_1002:
	v_pk_add_f32 v[114:115], v[116:117], v[118:119]
	v_lshlrev_b64 v[112:113], 12, v[112:113]
	v_add_f32_e32 v114, v114, v115
	v_mov_b32_e32 v115, v114
	s_nop 1
	v_permlane16_swap_b32_e32 v115, v114
	v_lshl_add_u64 v[112:113], s[8:9], 0, v[112:113]
	s_waitcnt lgkmcnt(0)
	v_add_f32_e32 v114, v114, v115
	v_mov_b32_e32 v115, v114
	s_nop 1
	v_permlane32_swap_b32_e32 v115, v114
	s_waitcnt lgkmcnt(0)
	v_add_f32_e32 v114, v114, v115
	v_fmamk_f32 v114, v114, 0x3a800000, v207
	v_mul_f32_e32 v115, 0x4b800000, v114
	v_cmp_gt_f32_e32 vcc, s49, v114
	s_nop 1
	v_cndmask_b32_e32 v114, v114, v115, vcc
	v_rsq_f32_e32 v116, v114
	v_lshl_add_u64 v[114:115], v[146:147], 2, v[112:113]
	v_mul_f32_e32 v112, 0x45800000, v116
	v_cndmask_b32_e32 v116, v116, v112, vcc
	v_pk_mul_f32 v[112:113], v[152:153], v[116:117] op_sel_hi:[1,0]
	v_pk_mul_f32 v[110:111], v[110:111], v[116:117] op_sel_hi:[1,0]
	v_pk_mul_f32 v[118:119], v[108:109], v[116:117] op_sel_hi:[1,0]
	v_pk_mul_f32 v[120:121], v[106:107], v[116:117] op_sel_hi:[1,0]
	v_pk_mul_f32 v[108:109], v[14:15], v[110:111]
	v_pk_mul_f32 v[106:107], v[12:13], v[112:113]
	v_pk_mul_f32 v[112:113], v[10:11], v[120:121]
	v_pk_mul_f32 v[110:111], v[8:9], v[118:119]
	global_store_dwordx4 v[114:115], v[106:109], off nt
	global_store_dwordx4 v[114:115], v[110:113], off offset:16 nt
	v_pk_mul_f32 v[102:103], v[102:103], v[116:117] op_sel_hi:[1,0]
	v_pk_mul_f32 v[106:107], v[104:105], v[116:117] op_sel_hi:[1,0]
	v_pk_mul_f32 v[104:105], v[6:7], v[102:103]
	v_pk_mul_f32 v[102:103], v[4:5], v[106:107]
	global_store_dwordx4 v[114:115], v[102:105], off offset:512 nt
	v_pk_mul_f32 v[98:99], v[98:99], v[116:117] op_sel_hi:[1,0]
	s_nop 0
	v_pk_mul_f32 v[102:103], v[100:101], v[116:117] op_sel_hi:[1,0]
	v_pk_mul_f32 v[100:101], v[2:3], v[98:99]
	v_pk_mul_f32 v[98:99], v[0:1], v[102:103]
	global_store_dwordx4 v[114:115], v[98:101], off offset:528 nt
	s_nop 1
	v_lshl_add_u64 v[98:99], v[136:137], 0, v[184:185]
	s_branch .LBB0_1005

.LBB0_1008:
	v_pk_add_f32 v[98:99], v[100:101], v[102:103]
	v_lshlrev_b64 v[96:97], 12, v[96:97]
	v_add_f32_e32 v98, v98, v99
	v_mov_b32_e32 v99, v98
	s_nop 1
	v_permlane16_swap_b32_e32 v99, v98
	v_lshl_add_u64 v[96:97], s[8:9], 0, v[96:97]
	s_waitcnt lgkmcnt(0)
	v_add_f32_e32 v98, v98, v99
	v_mov_b32_e32 v99, v98
	s_nop 1
	v_permlane32_swap_b32_e32 v99, v98
	s_waitcnt lgkmcnt(0)
	v_add_f32_e32 v98, v98, v99
	v_fmamk_f32 v98, v98, 0x3a800000, v207
	v_mul_f32_e32 v99, 0x4b800000, v98
	v_cmp_gt_f32_e32 vcc, s49, v98
	s_nop 1
	v_cndmask_b32_e32 v98, v98, v99, vcc
	v_rsq_f32_e32 v100, v98
	v_lshl_add_u64 v[98:99], v[146:147], 2, v[96:97]
	v_mul_f32_e32 v96, 0x45800000, v100
	v_cndmask_b32_e32 v100, v100, v96, vcc
	v_pk_mul_f32 v[96:97], v[154:155], v[100:101] op_sel_hi:[1,0]
	v_pk_mul_f32 v[94:95], v[94:95], v[100:101] op_sel_hi:[1,0]
	v_pk_mul_f32 v[102:103], v[92:93], v[100:101] op_sel_hi:[1,0]
	v_pk_mul_f32 v[104:105], v[90:91], v[100:101] op_sel_hi:[1,0]
	v_pk_mul_f32 v[92:93], v[14:15], v[94:95]
	v_pk_mul_f32 v[90:91], v[12:13], v[96:97]
	v_pk_mul_f32 v[96:97], v[10:11], v[104:105]
	v_pk_mul_f32 v[94:95], v[8:9], v[102:103]
	global_store_dwordx4 v[98:99], v[90:93], off nt
	global_store_dwordx4 v[98:99], v[94:97], off offset:16 nt
	v_pk_mul_f32 v[86:87], v[86:87], v[100:101] op_sel_hi:[1,0]
	v_pk_mul_f32 v[90:91], v[88:89], v[100:101] op_sel_hi:[1,0]
	v_pk_mul_f32 v[88:89], v[6:7], v[86:87]
	v_pk_mul_f32 v[86:87], v[4:5], v[90:91]
	global_store_dwordx4 v[98:99], v[86:89], off offset:512 nt
	v_pk_mul_f32 v[82:83], v[82:83], v[100:101] op_sel_hi:[1,0]
	s_nop 0
	v_pk_mul_f32 v[86:87], v[84:85], v[100:101] op_sel_hi:[1,0]
	v_pk_mul_f32 v[84:85], v[2:3], v[82:83]
	v_pk_mul_f32 v[82:83], v[0:1], v[86:87]
	global_store_dwordx4 v[98:99], v[82:85], off offset:528 nt
	s_nop 1
	v_lshl_add_u64 v[82:83], v[136:137], 0, v[186:187]
	s_branch .LBB0_1011

.LBB0_1014:
	v_pk_add_f32 v[82:83], v[84:85], v[86:87]
	v_lshlrev_b64 v[80:81], 12, v[80:81]
	v_add_f32_e32 v82, v82, v83
	v_mov_b32_e32 v83, v82
	s_nop 1
	v_permlane16_swap_b32_e32 v83, v82
	v_lshl_add_u64 v[80:81], s[8:9], 0, v[80:81]
	s_waitcnt lgkmcnt(0)
	v_add_f32_e32 v82, v82, v83
	v_mov_b32_e32 v83, v82
	s_nop 1
	v_permlane32_swap_b32_e32 v83, v82
	s_waitcnt lgkmcnt(0)
	v_add_f32_e32 v82, v82, v83
	v_fmamk_f32 v82, v82, 0x3a800000, v207
	v_mul_f32_e32 v83, 0x4b800000, v82
	v_cmp_gt_f32_e32 vcc, s49, v82
	s_nop 1
	v_cndmask_b32_e32 v82, v82, v83, vcc
	v_rsq_f32_e32 v84, v82
	v_lshl_add_u64 v[82:83], v[146:147], 2, v[80:81]
	v_mul_f32_e32 v80, 0x45800000, v84
	v_cndmask_b32_e32 v84, v84, v80, vcc
	v_pk_mul_f32 v[80:81], v[156:157], v[84:85] op_sel_hi:[1,0]
	v_pk_mul_f32 v[78:79], v[78:79], v[84:85] op_sel_hi:[1,0]
	v_pk_mul_f32 v[86:87], v[76:77], v[84:85] op_sel_hi:[1,0]
	v_pk_mul_f32 v[88:89], v[74:75], v[84:85] op_sel_hi:[1,0]
	v_pk_mul_f32 v[76:77], v[14:15], v[78:79]
	v_pk_mul_f32 v[74:75], v[12:13], v[80:81]
	v_pk_mul_f32 v[80:81], v[10:11], v[88:89]
	v_pk_mul_f32 v[78:79], v[8:9], v[86:87]
	global_store_dwordx4 v[82:83], v[74:77], off nt
	global_store_dwordx4 v[82:83], v[78:81], off offset:16 nt
	v_pk_mul_f32 v[70:71], v[70:71], v[84:85] op_sel_hi:[1,0]
	v_pk_mul_f32 v[74:75], v[72:73], v[84:85] op_sel_hi:[1,0]
	v_pk_mul_f32 v[72:73], v[6:7], v[70:71]
	v_pk_mul_f32 v[70:71], v[4:5], v[74:75]
	global_store_dwordx4 v[82:83], v[70:73], off offset:512 nt
	v_pk_mul_f32 v[66:67], v[66:67], v[84:85] op_sel_hi:[1,0]
	s_nop 0
	v_pk_mul_f32 v[70:71], v[68:69], v[84:85] op_sel_hi:[1,0]
	v_pk_mul_f32 v[68:69], v[2:3], v[66:67]
	v_pk_mul_f32 v[66:67], v[0:1], v[70:71]
	global_store_dwordx4 v[82:83], v[66:69], off offset:528 nt
	s_nop 1
	v_lshl_add_u64 v[66:67], v[136:137], 0, v[188:189]
	s_branch .LBB0_1017

.LBB0_1020:
	v_pk_add_f32 v[66:67], v[68:69], v[70:71]
	v_lshlrev_b64 v[64:65], 12, v[64:65]
	v_add_f32_e32 v66, v66, v67
	v_mov_b32_e32 v67, v66
	s_nop 1
	v_permlane16_swap_b32_e32 v67, v66
	v_lshl_add_u64 v[64:65], s[8:9], 0, v[64:65]
	s_waitcnt lgkmcnt(0)
	v_add_f32_e32 v66, v66, v67
	v_mov_b32_e32 v67, v66
	s_nop 1
	v_permlane32_swap_b32_e32 v67, v66
	s_waitcnt lgkmcnt(0)
	v_add_f32_e32 v66, v66, v67
	v_fmamk_f32 v66, v66, 0x3a800000, v207
	v_mul_f32_e32 v67, 0x4b800000, v66
	v_cmp_gt_f32_e32 vcc, s49, v66
	s_nop 1
	v_cndmask_b32_e32 v66, v66, v67, vcc
	v_rsq_f32_e32 v68, v66
	v_lshl_add_u64 v[66:67], v[146:147], 2, v[64:65]
	v_mul_f32_e32 v64, 0x45800000, v68
	v_cndmask_b32_e32 v68, v68, v64, vcc
	v_pk_mul_f32 v[64:65], v[158:159], v[68:69] op_sel_hi:[1,0]
	v_pk_mul_f32 v[62:63], v[62:63], v[68:69] op_sel_hi:[1,0]
	v_pk_mul_f32 v[70:71], v[60:61], v[68:69] op_sel_hi:[1,0]
	v_pk_mul_f32 v[72:73], v[58:59], v[68:69] op_sel_hi:[1,0]
	v_pk_mul_f32 v[60:61], v[14:15], v[62:63]
	v_pk_mul_f32 v[58:59], v[12:13], v[64:65]
	v_pk_mul_f32 v[64:65], v[10:11], v[72:73]
	v_pk_mul_f32 v[62:63], v[8:9], v[70:71]
	global_store_dwordx4 v[66:67], v[58:61], off nt
	global_store_dwordx4 v[66:67], v[62:65], off offset:16 nt
	v_pk_mul_f32 v[54:55], v[54:55], v[68:69] op_sel_hi:[1,0]
	v_pk_mul_f32 v[58:59], v[56:57], v[68:69] op_sel_hi:[1,0]
	v_pk_mul_f32 v[56:57], v[6:7], v[54:55]
	v_pk_mul_f32 v[54:55], v[4:5], v[58:59]
	global_store_dwordx4 v[66:67], v[54:57], off offset:512 nt
	v_pk_mul_f32 v[50:51], v[50:51], v[68:69] op_sel_hi:[1,0]
	s_nop 0
	v_pk_mul_f32 v[54:55], v[52:53], v[68:69] op_sel_hi:[1,0]
	v_pk_mul_f32 v[52:53], v[2:3], v[50:51]
	v_pk_mul_f32 v[50:51], v[0:1], v[54:55]
	global_store_dwordx4 v[66:67], v[50:53], off offset:528 nt
	s_nop 1
	v_lshl_add_u64 v[50:51], v[136:137], 0, v[190:191]
	s_branch .LBB0_1023

.LBB0_1026:
	v_pk_add_f32 v[50:51], v[52:53], v[54:55]
	v_lshlrev_b64 v[48:49], 12, v[48:49]
	v_add_f32_e32 v50, v50, v51
	v_mov_b32_e32 v51, v50
	s_nop 1
	v_permlane16_swap_b32_e32 v51, v50
	v_lshl_add_u64 v[48:49], s[8:9], 0, v[48:49]
	s_waitcnt lgkmcnt(0)
	v_add_f32_e32 v50, v50, v51
	v_mov_b32_e32 v51, v50
	s_nop 1
	v_permlane32_swap_b32_e32 v51, v50
	s_waitcnt lgkmcnt(0)
	v_add_f32_e32 v50, v50, v51
	v_fmamk_f32 v50, v50, 0x3a800000, v207
	v_mul_f32_e32 v51, 0x4b800000, v50
	v_cmp_gt_f32_e32 vcc, s49, v50
	s_nop 1
	v_cndmask_b32_e32 v50, v50, v51, vcc
	v_rsq_f32_e32 v52, v50
	v_lshl_add_u64 v[50:51], v[146:147], 2, v[48:49]
	v_mul_f32_e32 v48, 0x45800000, v52
	v_cndmask_b32_e32 v52, v52, v48, vcc
	v_pk_mul_f32 v[48:49], v[160:161], v[52:53] op_sel_hi:[1,0]
	v_pk_mul_f32 v[46:47], v[46:47], v[52:53] op_sel_hi:[1,0]
	v_pk_mul_f32 v[54:55], v[44:45], v[52:53] op_sel_hi:[1,0]
	v_pk_mul_f32 v[56:57], v[42:43], v[52:53] op_sel_hi:[1,0]
	v_pk_mul_f32 v[44:45], v[14:15], v[46:47]
	v_pk_mul_f32 v[42:43], v[12:13], v[48:49]
	v_pk_mul_f32 v[48:49], v[10:11], v[56:57]
	v_pk_mul_f32 v[46:47], v[8:9], v[54:55]
	global_store_dwordx4 v[50:51], v[42:45], off nt
	global_store_dwordx4 v[50:51], v[46:49], off offset:16 nt
	v_pk_mul_f32 v[38:39], v[38:39], v[52:53] op_sel_hi:[1,0]
	v_pk_mul_f32 v[42:43], v[40:41], v[52:53] op_sel_hi:[1,0]
	v_pk_mul_f32 v[40:41], v[6:7], v[38:39]
	v_pk_mul_f32 v[38:39], v[4:5], v[42:43]
	global_store_dwordx4 v[50:51], v[38:41], off offset:512 nt
	v_pk_mul_f32 v[34:35], v[34:35], v[52:53] op_sel_hi:[1,0]
	s_nop 0
	v_pk_mul_f32 v[38:39], v[36:37], v[52:53] op_sel_hi:[1,0]
	v_pk_mul_f32 v[36:37], v[2:3], v[34:35]
	v_pk_mul_f32 v[34:35], v[0:1], v[38:39]
	global_store_dwordx4 v[50:51], v[34:37], off offset:528 nt
	s_nop 1
	v_lshl_add_u64 v[34:35], v[136:137], 0, v[192:193]
	s_branch .LBB0_1029

.LBB0_1032:
	v_pk_add_f32 v[34:35], v[36:37], v[38:39]
	v_lshlrev_b64 v[32:33], 12, v[32:33]
	v_add_f32_e32 v34, v34, v35
	v_mov_b32_e32 v35, v34
	s_nop 1
	v_permlane16_swap_b32_e32 v35, v34
	v_lshl_add_u64 v[32:33], s[8:9], 0, v[32:33]
	v_lshl_add_u64 v[40:41], v[146:147], 2, v[32:33]
	s_waitcnt lgkmcnt(0)
	v_add_f32_e32 v34, v34, v35
	v_mov_b32_e32 v35, v34
	s_nop 1
	v_permlane32_swap_b32_e32 v35, v34
	s_waitcnt lgkmcnt(0)
	v_add_f32_e32 v34, v34, v35
	v_fmamk_f32 v34, v34, 0x3a800000, v207
	v_mul_f32_e32 v35, 0x4b800000, v34
	v_cmp_gt_f32_e32 vcc, s49, v34
	s_nop 1
	v_cndmask_b32_e32 v34, v34, v35, vcc
	v_rsq_f32_e32 v34, v34
	s_nop 0
	v_mul_f32_e32 v32, 0x45800000, v34
	v_cndmask_b32_e32 v42, v34, v32, vcc
	v_pk_mul_f32 v[28:29], v[28:29], v[42:43] op_sel_hi:[1,0]
	v_pk_mul_f32 v[32:33], v[172:173], v[42:43] op_sel_hi:[1,0]
	v_pk_mul_f32 v[34:35], v[168:169], v[42:43] op_sel_hi:[1,0]
	v_pk_mul_f32 v[38:39], v[10:11], v[28:29]
	v_pk_mul_f32 v[28:29], v[24:25], v[42:43] op_sel_hi:[1,0]
	v_pk_mul_f32 v[22:23], v[22:23], v[42:43] op_sel_hi:[1,0]
	v_pk_mul_f32 v[36:37], v[164:165], v[42:43] op_sel_hi:[1,0]
	v_pk_mul_f32 v[34:35], v[14:15], v[34:35]
	v_pk_mul_f32 v[32:33], v[12:13], v[32:33]
	v_pk_mul_f32 v[24:25], v[6:7], v[22:23]
	v_pk_mul_f32 v[22:23], v[4:5], v[28:29]
	v_pk_mul_f32 v[36:37], v[8:9], v[36:37]
	global_store_dwordx4 v[40:41], v[32:35], off nt
	global_store_dwordx4 v[40:41], v[36:39], off offset:16 nt
	global_store_dwordx4 v[40:41], v[22:25], off offset:512 nt
	v_pk_mul_f32 v[18:19], v[18:19], v[42:43] op_sel_hi:[1,0]
	s_nop 0
	v_pk_mul_f32 v[22:23], v[20:21], v[42:43] op_sel_hi:[1,0]
	v_pk_mul_f32 v[20:21], v[2:3], v[18:19]
	v_pk_mul_f32 v[18:19], v[0:1], v[22:23]
	v_lshl_add_u64 v[22:23], v[136:137], 0, v[194:195]
	global_store_dwordx4 v[40:41], v[18:21], off offset:528 nt
	s_branch .LBB0_1035
